# P3 branch-projection epilogue: gate loads de-serialised (12-slot prefetch ring with counted vmcnt instead of load+vmcnt(0) per group)
# speedup vs baseline: 1.0134x; 1.0022x over previous
; __device__ __forceinline__ unsigned cvt_pk_bf16(float lo, float hi) { unsigned r; asm volatile("v_cvt_pk_bf16_f32 %0, %1, %2" : "=v"(r) : "v"(lo), "v"(hi)); return r; }
; __device__ __forceinline__ float bf_lo(unsigned u) { return __uint_as_float(u << 16); }
; __device__ __forceinline__ float bf_hi(unsigned u) { return __uint_as_float(u & 0xffff0000u); }
;     __device__ __forceinline__ void operator()(f32x4 (&acc)[2][2][4][2], const Unit& u, int wr, int wc, int fr, int fq) const {
;     ...
;             for (int m = 0; m < 4; ++m) { bf16_t* hrow = H + (size_t)(row0 + ai * HALF + m * 16) * INC;
; #pragma unroll
;                 for (int bj = 0; bj < 2; ++bj) { const int col = col0 + bj * HALF;
;                     if (br < 2) {
;                         const u32x4 ga = *(const u32x4*)(hrow + C_GL + br * 1024 + col), gb = *(const u32x4*)(hrow + C_GL + (br + 1) * 1024 + col);
;                         float r[8];
; #pragma unroll
;                         for (int e = 0; e < 4; ++e) { const unsigned wa = ga[e], wb = gb[e];
;                             r[2 * e]     = bf_lo(wa) * __builtin_amdgcn_rcpf(bf_lo(wb));
;                             r[2 * e + 1] = bf_hi(wa) * __builtin_amdgcn_rcpf(bf_hi(wb)); }
;                         acc[ai][bj][m][0] *= (f32x4){r[0], r[1], r[2], r[3]}; acc[ai][bj][m][1] *= (f32x4){r[4], r[5], r[6], r[7]};
;                     } else {
;                         const u32x4 gc = *(const u32x4*)(hrow + C_GL + 2048 + col);
;                         f32x4 g0, g1;
;                         g0[0] = bf_lo(gc.x); g0[1] = bf_hi(gc.x); g0[2] = bf_lo(gc.y); g0[3] = bf_hi(gc.y);
;                         g1[0] = bf_lo(gc.z); g1[1] = bf_hi(gc.z); g1[2] = bf_lo(gc.w); g1[3] = bf_hi(gc.w);
;                         const f32x4 v0 = acc[ai][bj][m][0] * g0, v1 = acc[ai][bj][m][1] * g1;
;                         u32x4 w; w.x = cvt_pk_bf16(v0[0], v0[1]); w.y = cvt_pk_bf16(v0[2], v0[3]); w.z = cvt_pk_bf16(v1[0], v1[1]); w.w = cvt_pk_bf16(v1[2], v1[3]);
;                         *(u32x4*)(hrow + C_AZ + col) = w;
.LBB0_661:
	v_lshl_or_b32 v156, s34, 8, v182
	v_lshl_add_u32 v184, s4, 8, v178
	s_cmp_gt_i32 s5, 1
	v_mov_b64_e32 v[140:141], s[58:59]
	s_cselect_b64 s[76:77], -1, 0
	v_mad_i64_i32 v[140:141], s[6:7], v184, s18, v[140:141]
	v_ashrrev_i32_e32 v157, 31, v156
	v_lshl_add_u64 v[150:151], v[140:141], 0, s[52:53]
	v_lshl_add_u64 v[148:149], v[140:141], 0, s[54:55]
	s_mov_b64 s[40:41], -1
	s_and_b64 vcc, exec, s[76:77]
	v_lshlrev_b64 v[158:159], 1, v[156:157]
	s_cbranch_vccz .LBB0_663
	v_lshl_add_u64 v[142:143], v[150:151], 0, v[158:159]
	v_mov_b32_e32 v186, v142
	v_mov_b32_e32 v187, v143
	s_mov_b32 s8, 0x48000
	s_mov_b32 s9, 0
	s_mov_b32 s10, 0x168000
	s_mov_b32 s11, 0
	global_load_dwordx4 v[188:191], v[186:187], off
	global_load_dwordx4 v[192:195], v[186:187], off offset:256
	v_lshl_add_u64 v[186:187], v[186:187], 0, s[8:9]
	global_load_dwordx4 v[196:199], v[186:187], off
	global_load_dwordx4 v[212:215], v[186:187], off offset:256
	v_lshl_add_u64 v[186:187], v[186:187], 0, s[8:9]
	global_load_dwordx4 v[216:219], v[186:187], off
	global_load_dwordx4 v[220:223], v[186:187], off offset:256
	v_lshl_add_u64 v[186:187], v[186:187], 0, s[8:9]
	global_load_dwordx4 v[224:227], v[186:187], off
	global_load_dwordx4 v[228:231], v[186:187], off offset:256
	v_lshl_add_u64 v[186:187], v[186:187], 0, s[10:11]
	global_load_dwordx4 v[232:235], v[186:187], off
	global_load_dwordx4 v[236:239], v[186:187], off offset:256
	v_lshl_add_u64 v[186:187], v[186:187], 0, s[8:9]
	global_load_dwordx4 v[240:243], v[186:187], off
	global_load_dwordx4 v[244:247], v[186:187], off offset:256
	v_lshl_add_u64 v[186:187], v[186:187], 0, s[8:9]
	s_mov_b64 s[40:41], 0
	s_waitcnt vmcnt(11)
	v_mov_b32_e32 v142, v188
	v_mov_b32_e32 v143, v189
	v_mov_b32_e32 v144, v190
	v_mov_b32_e32 v145, v191
	global_load_dwordx4 v[188:191], v[186:187], off
	v_lshlrev_b32_e32 v146, 16, v142
	v_and_b32_e32 v147, 0xffff0000, v142
	v_lshlrev_b32_e32 v142, 16, v143
	v_and_b32_e32 v143, 0xffff0000, v143
	v_lshlrev_b32_e32 v152, 16, v144
	v_and_b32_e32 v153, 0xffff0000, v144
	v_lshlrev_b32_e32 v144, 16, v145
	v_and_b32_e32 v145, 0xffff0000, v145
	v_pk_mul_f32 v[154:155], v[128:129], v[142:143]
	v_pk_mul_f32 v[142:143], v[126:127], v[146:147]
	v_pk_mul_f32 v[146:147], v[124:125], v[144:145]
	v_pk_mul_f32 v[144:145], v[122:123], v[152:153]
	v_cvt_pk_bf16_f32 v142, v142, v143
	v_cvt_pk_bf16_f32 v143, v154, v155
	s_nop 0
	v_cvt_pk_bf16_f32 v144, v144, v145
	v_cvt_pk_bf16_f32 v145, v146, v147
	v_lshl_add_u64 v[146:147], v[148:149], 0, v[158:159]
	global_store_dwordx4 v[146:147], v[142:145], off
.LBB0_663:
	s_lshl_b32 s34, s5, 10
	s_ashr_i32 s35, s34, 31
	v_lshl_add_u64 v[140:141], s[34:35], 1, v[140:141]
	v_lshl_add_u64 v[142:143], v[140:141], 0, s[60:61]
	v_mov_b32_e32 v140, 0
	s_andn2_b64 vcc, exec, s[40:41]
	v_lshl_add_u64 v[152:153], v[156:157], 1, v[142:143]
	v_mov_b32_e32 v141, 0
	v_mov_b32_e32 v146, 0
	v_mov_b32_e32 v147, 0
	v_mov_b32_e32 v142, 0
	v_mov_b32_e32 v143, 0
	v_mov_b32_e32 v144, 0
	v_mov_b32_e32 v145, 0
	s_cbranch_vccnz .LBB0_665
	v_mov_b32_e32 v186, v152
	v_mov_b32_e32 v187, v153
	s_mov_b32 s8, 0x48000
	s_mov_b32 s9, 0
	s_mov_b32 s10, 0x168000
	s_mov_b32 s11, 0
	global_load_dwordx4 v[188:191], v[186:187], off
	global_load_dwordx4 v[192:195], v[186:187], off offset:2048
	global_load_dwordx4 v[196:199], v[186:187], off offset:256
	global_load_dwordx4 v[212:215], v[186:187], off offset:2304
	v_lshl_add_u64 v[186:187], v[186:187], 0, s[8:9]
	global_load_dwordx4 v[216:219], v[186:187], off
	global_load_dwordx4 v[220:223], v[186:187], off offset:2048
	global_load_dwordx4 v[224:227], v[186:187], off offset:256
	global_load_dwordx4 v[228:231], v[186:187], off offset:2304
	v_lshl_add_u64 v[186:187], v[186:187], 0, s[8:9]
	global_load_dwordx4 v[232:235], v[186:187], off
	global_load_dwordx4 v[236:239], v[186:187], off offset:2048
	global_load_dwordx4 v[240:243], v[186:187], off offset:256
	global_load_dwordx4 v[244:247], v[186:187], off offset:2304
	v_lshl_add_u64 v[186:187], v[186:187], 0, s[8:9]
	s_waitcnt vmcnt(10)
	v_mov_b32_e32 v140, v188
	v_mov_b32_e32 v141, v189
	v_mov_b32_e32 v142, v190
	v_mov_b32_e32 v143, v191
	v_mov_b32_e32 v144, v192
	v_mov_b32_e32 v145, v193
	v_mov_b32_e32 v146, v194
	v_mov_b32_e32 v147, v195
	global_load_dwordx4 v[188:191], v[186:187], off
	global_load_dwordx4 v[192:195], v[186:187], off offset:2048
	v_lshlrev_b32_e32 v160, 16, v140
	v_lshlrev_b32_e32 v154, 16, v144
	v_and_b32_e32 v144, 0xffff0000, v144
	v_and_b32_e32 v161, 0xffff0000, v140
	v_lshlrev_b32_e32 v140, 16, v145
	v_rcp_f32_e32 v155, v144
	v_rcp_f32_e32 v144, v140
	v_and_b32_e32 v140, 0xffff0000, v145
	v_rcp_f32_e32 v145, v140
	v_lshlrev_b32_e32 v140, 16, v141
	v_and_b32_e32 v141, 0xffff0000, v141
	v_rcp_f32_e32 v154, v154
	v_pk_mul_f32 v[140:141], v[144:145], v[140:141]
	v_lshlrev_b32_e32 v144, 16, v146
	v_and_b32_e32 v145, 0xffff0000, v146
	v_rcp_f32_e32 v144, v144
	v_rcp_f32_e32 v145, v145
	v_pk_mul_f32 v[154:155], v[154:155], v[160:161]
	v_lshlrev_b32_e32 v160, 16, v142
	v_and_b32_e32 v161, 0xffff0000, v142
	v_lshlrev_b32_e32 v142, 16, v147
	v_pk_mul_f32 v[160:161], v[144:145], v[160:161]
	v_rcp_f32_e32 v144, v142
	v_and_b32_e32 v142, 0xffff0000, v147
	v_rcp_f32_e32 v145, v142
	v_lshlrev_b32_e32 v142, 16, v143
	v_and_b32_e32 v143, 0xffff0000, v143
	v_pk_mul_f32 v[146:147], v[144:145], v[142:143]
	v_pk_mul_f32 v[144:145], v[128:129], v[140:141]
	v_pk_mul_f32 v[142:143], v[126:127], v[154:155]
	v_pk_mul_f32 v[146:147], v[124:125], v[146:147]
	v_pk_mul_f32 v[140:141], v[122:123], v[160:161]
; __device__ __forceinline__ unsigned cvt_pk_bf16(float lo, float hi) { unsigned r; asm volatile("v_cvt_pk_bf16_f32 %0, %1, %2" : "=v"(r) : "v"(lo), "v"(hi)); return r; }
; __device__ __forceinline__ float bf_lo(unsigned u) { return __uint_as_float(u << 16); }
; __device__ __forceinline__ float bf_hi(unsigned u) { return __uint_as_float(u & 0xffff0000u); }
;     __device__ __forceinline__ void operator()(f32x4 (&acc)[2][2][4][2], const Unit& u, int wr, int wc, int fr, int fq) const {
;     ...
;             for (int m = 0; m < 4; ++m) { bf16_t* hrow = H + (size_t)(row0 + ai * HALF + m * 16) * INC;
; #pragma unroll
;                 for (int bj = 0; bj < 2; ++bj) { const int col = col0 + bj * HALF;
;                     if (br < 2) {
;                         const u32x4 ga = *(const u32x4*)(hrow + C_GL + br * 1024 + col), gb = *(const u32x4*)(hrow + C_GL + (br + 1) * 1024 + col);
;                         float r[8];
; #pragma unroll
;                         for (int e = 0; e < 4; ++e) { const unsigned wa = ga[e], wb = gb[e];
;                             r[2 * e]     = bf_lo(wa) * __builtin_amdgcn_rcpf(bf_lo(wb));
;                             r[2 * e + 1] = bf_hi(wa) * __builtin_amdgcn_rcpf(bf_hi(wb)); }
;                         acc[ai][bj][m][0] *= (f32x4){r[0], r[1], r[2], r[3]}; acc[ai][bj][m][1] *= (f32x4){r[4], r[5], r[6], r[7]};
;                     } else {
;                         const u32x4 gc = *(const u32x4*)(hrow + C_GL + 2048 + col);
;                         f32x4 g0, g1;
;                         g0[0] = bf_lo(gc.x); g0[1] = bf_hi(gc.x); g0[2] = bf_lo(gc.y); g0[3] = bf_hi(gc.y);
;                         g1[0] = bf_lo(gc.z); g1[1] = bf_hi(gc.z); g1[2] = bf_lo(gc.w); g1[3] = bf_hi(gc.w);
;                         const f32x4 v0 = acc[ai][bj][m][0] * g0, v1 = acc[ai][bj][m][1] * g1;
;                         u32x4 w; w.x = cvt_pk_bf16(v0[0], v0[1]); w.y = cvt_pk_bf16(v0[2], v0[3]); w.z = cvt_pk_bf16(v1[0], v1[1]); w.w = cvt_pk_bf16(v1[2], v1[3]);
;                         *(u32x4*)(hrow + C_AZ + col) = w;
;                         acc[ai][bj][m][0] = (f32x4){0.f, 0.f, 0.f, 0.f}; acc[ai][bj][m][1] = (f32x4){0.f, 0.f, 0.f, 0.f};
;                     }
.LBB0_665:
	v_or_b32_e32 v122, 0x80, v156
	v_ashrrev_i32_e32 v123, 31, v122
	v_cndmask_b32_e64 v124, 0, 1, s[76:77]
	s_mov_b64 s[78:79], -1
	v_cmp_ne_u32_e64 s[40:41], 1, v124
	s_andn2_b64 vcc, exec, s[76:77]
	v_lshlrev_b64 v[160:161], 1, v[122:123]
	s_cbranch_vccnz .LBB0_667
	v_lshl_add_u64 v[122:123], v[150:151], 0, v[160:161]
	v_lshl_add_u64 v[126:127], v[148:149], 0, v[160:161]
	s_mov_b64 s[78:79], 0
	s_waitcnt vmcnt(12)
	v_mov_b32_e32 v122, v192
	v_mov_b32_e32 v123, v193
	v_mov_b32_e32 v124, v194
	v_mov_b32_e32 v125, v195
	global_load_dwordx4 v[192:195], v[186:187], off offset:256
	v_lshl_add_u64 v[186:187], v[186:187], 0, s[8:9]
	v_lshlrev_b32_e32 v128, 16, v122
	v_and_b32_e32 v129, 0xffff0000, v122
	v_lshlrev_b32_e32 v122, 16, v123
	v_and_b32_e32 v123, 0xffff0000, v123
	v_lshlrev_b32_e32 v148, 16, v124
	v_and_b32_e32 v149, 0xffff0000, v124
	v_lshlrev_b32_e32 v124, 16, v125
	v_and_b32_e32 v125, 0xffff0000, v125
	v_pk_mul_f32 v[150:151], v[120:121], v[122:123]
	v_pk_mul_f32 v[122:123], v[118:119], v[128:129]
	v_pk_mul_f32 v[128:129], v[116:117], v[124:125]
	v_pk_mul_f32 v[124:125], v[114:115], v[148:149]
	v_cvt_pk_bf16_f32 v122, v122, v123
	v_cvt_pk_bf16_f32 v123, v150, v151
	s_nop 0
	v_cvt_pk_bf16_f32 v124, v124, v125
	v_cvt_pk_bf16_f32 v125, v128, v129
	global_store_dwordx4 v[126:127], v[122:125], off
.LBB0_667:
	s_nop 1
	v_mov_b32_e32 v122, 0
	s_andn2_b64 vcc, exec, s[78:79]
	v_mov_b32_e32 v123, 0
	v_mov_b32_e32 v128, 0
	v_mov_b32_e32 v129, 0
	v_mov_b32_e32 v124, 0
	v_mov_b32_e32 v125, 0
	v_mov_b32_e32 v126, 0
	v_mov_b32_e32 v127, 0
	s_cbranch_vccnz .LBB0_669
	s_waitcnt vmcnt(10)
	v_mov_b32_e32 v122, v196
	v_mov_b32_e32 v123, v197
	v_mov_b32_e32 v124, v198
	v_mov_b32_e32 v125, v199
	v_mov_b32_e32 v126, v212
	v_mov_b32_e32 v127, v213
	v_mov_b32_e32 v128, v214
	v_mov_b32_e32 v129, v215
	global_load_dwordx4 v[196:199], v[186:187], off offset:256
	global_load_dwordx4 v[212:215], v[186:187], off offset:2304
	v_lshl_add_u64 v[186:187], v[186:187], 0, s[10:11]
	v_lshlrev_b32_e32 v150, 16, v122
	v_lshlrev_b32_e32 v148, 16, v126
	v_and_b32_e32 v126, 0xffff0000, v126
	v_and_b32_e32 v151, 0xffff0000, v122
	v_lshlrev_b32_e32 v122, 16, v127
	v_rcp_f32_e32 v149, v126
	v_rcp_f32_e32 v126, v122
	v_and_b32_e32 v122, 0xffff0000, v127
	v_rcp_f32_e32 v127, v122
	v_lshlrev_b32_e32 v122, 16, v123
	v_and_b32_e32 v123, 0xffff0000, v123
	v_rcp_f32_e32 v148, v148
	v_pk_mul_f32 v[122:123], v[126:127], v[122:123]
	v_lshlrev_b32_e32 v126, 16, v128
	v_and_b32_e32 v127, 0xffff0000, v128
	v_rcp_f32_e32 v126, v126
	v_rcp_f32_e32 v127, v127
	v_pk_mul_f32 v[148:149], v[148:149], v[150:151]
	v_lshlrev_b32_e32 v150, 16, v124
	v_and_b32_e32 v151, 0xffff0000, v124
	v_lshlrev_b32_e32 v124, 16, v129
	v_pk_mul_f32 v[150:151], v[126:127], v[150:151]
	v_rcp_f32_e32 v126, v124
	v_and_b32_e32 v124, 0xffff0000, v129
	v_rcp_f32_e32 v127, v124
	v_lshlrev_b32_e32 v124, 16, v125
	v_and_b32_e32 v125, 0xffff0000, v125
	v_pk_mul_f32 v[128:129], v[126:127], v[124:125]
	v_pk_mul_f32 v[126:127], v[120:121], v[122:123]
	v_pk_mul_f32 v[124:125], v[118:119], v[148:149]
	v_pk_mul_f32 v[128:129], v[116:117], v[128:129]
	v_pk_mul_f32 v[122:123], v[114:115], v[150:151]
.LBB0_669:
	v_or_b32_e32 v116, 16, v184
	v_mov_b64_e32 v[114:115], s[58:59]
	v_mad_i64_i32 v[118:119], s[4:5], v116, s18, v[114:115]
	v_lshl_add_u64 v[116:117], v[118:119], 0, s[52:53]
	v_lshl_add_u64 v[114:115], v[118:119], 0, s[54:55]
	s_and_b64 vcc, exec, s[40:41]
	s_mov_b64 s[76:77], -1
	s_cbranch_vccnz .LBB0_671
	v_lshl_add_u64 v[120:121], v[116:117], 0, v[158:159]
	s_mov_b64 s[76:77], 0
	s_waitcnt vmcnt(13)
	v_mov_b32_e32 v148, v196
	v_mov_b32_e32 v149, v197
	v_mov_b32_e32 v150, v198
	v_mov_b32_e32 v151, v199
	global_load_dwordx4 v[196:199], v[186:187], off
	v_lshlrev_b32_e32 v120, 16, v148
	v_and_b32_e32 v121, 0xffff0000, v148
	v_lshlrev_b32_e32 v148, 16, v149
	v_and_b32_e32 v149, 0xffff0000, v149
	v_lshlrev_b32_e32 v152, 16, v150
	v_and_b32_e32 v153, 0xffff0000, v150
	v_lshlrev_b32_e32 v150, 16, v151
	v_and_b32_e32 v151, 0xffff0000, v151
	v_pk_mul_f32 v[120:121], v[110:111], v[120:121]
	v_pk_mul_f32 v[154:155], v[112:113], v[148:149]
	v_pk_mul_f32 v[162:163], v[108:109], v[150:151]
	v_pk_mul_f32 v[150:151], v[106:107], v[152:153]
	v_cvt_pk_bf16_f32 v148, v120, v121
	v_lshl_add_u64 v[120:121], v[114:115], 0, v[158:159]
	v_cvt_pk_bf16_f32 v149, v154, v155
	v_cvt_pk_bf16_f32 v150, v150, v151
	v_cvt_pk_bf16_f32 v151, v162, v163
	global_store_dwordx4 v[120:121], v[148:151], off
.LBB0_671:
	v_lshl_add_u64 v[118:119], s[34:35], 1, v[118:119]
	v_lshl_add_u64 v[118:119], v[118:119], 0, s[60:61]
	v_mov_b32_e32 v148, 0
	s_andn2_b64 vcc, exec, s[76:77]
	v_lshl_add_u64 v[118:119], v[156:157], 1, v[118:119]
	v_mov_b32_e32 v149, 0
	v_mov_b32_e32 v154, 0
	v_mov_b32_e32 v155, 0
	v_mov_b32_e32 v150, 0
	v_mov_b32_e32 v151, 0
	v_mov_b32_e32 v152, 0
	v_mov_b32_e32 v153, 0
	s_cbranch_vccnz .LBB0_673
	s_waitcnt vmcnt(10)
	v_mov_b32_e32 v148, v216
	v_mov_b32_e32 v149, v217
	v_mov_b32_e32 v150, v218
	v_mov_b32_e32 v151, v219
	v_mov_b32_e32 v152, v220
	v_mov_b32_e32 v153, v221
	v_mov_b32_e32 v154, v222
	v_mov_b32_e32 v155, v223
	global_load_dwordx4 v[216:219], v[186:187], off
	global_load_dwordx4 v[220:223], v[186:187], off offset:2048
	v_lshlrev_b32_e32 v162, 16, v148
	v_and_b32_e32 v163, 0xffff0000, v148
	v_lshlrev_b32_e32 v148, 16, v153
	v_lshlrev_b32_e32 v120, 16, v152
	v_and_b32_e32 v121, 0xffff0000, v152
	v_rcp_f32_e32 v152, v148
	v_and_b32_e32 v148, 0xffff0000, v153
	v_rcp_f32_e32 v153, v148
	v_lshlrev_b32_e32 v148, 16, v149
	v_and_b32_e32 v149, 0xffff0000, v149
	v_rcp_f32_e32 v120, v120
	v_rcp_f32_e32 v121, v121
	v_pk_mul_f32 v[148:149], v[152:153], v[148:149]
	v_lshlrev_b32_e32 v152, 16, v154
	v_and_b32_e32 v153, 0xffff0000, v154
	v_rcp_f32_e32 v152, v152
	v_rcp_f32_e32 v153, v153
	v_pk_mul_f32 v[120:121], v[120:121], v[162:163]
	v_lshlrev_b32_e32 v162, 16, v150
	v_and_b32_e32 v163, 0xffff0000, v150
	v_lshlrev_b32_e32 v150, 16, v155
	v_pk_mul_f32 v[162:163], v[152:153], v[162:163]
	v_rcp_f32_e32 v152, v150
	v_and_b32_e32 v150, 0xffff0000, v155
	v_rcp_f32_e32 v153, v150
	v_lshlrev_b32_e32 v150, 16, v151
	v_and_b32_e32 v151, 0xffff0000, v151
	v_pk_mul_f32 v[154:155], v[152:153], v[150:151]
	v_pk_mul_f32 v[152:153], v[112:113], v[148:149]
	v_pk_mul_f32 v[150:151], v[110:111], v[120:121]
	v_pk_mul_f32 v[154:155], v[108:109], v[154:155]
	v_pk_mul_f32 v[148:149], v[106:107], v[162:163]
; __device__ __forceinline__ unsigned cvt_pk_bf16(float lo, float hi) { unsigned r; asm volatile("v_cvt_pk_bf16_f32 %0, %1, %2" : "=v"(r) : "v"(lo), "v"(hi)); return r; }
; __device__ __forceinline__ float bf_lo(unsigned u) { return __uint_as_float(u << 16); }
; __device__ __forceinline__ float bf_hi(unsigned u) { return __uint_as_float(u & 0xffff0000u); }
;     __device__ __forceinline__ void operator()(f32x4 (&acc)[2][2][4][2], const Unit& u, int wr, int wc, int fr, int fq) const {
;     ...
;             for (int m = 0; m < 4; ++m) { bf16_t* hrow = H + (size_t)(row0 + ai * HALF + m * 16) * INC;
; #pragma unroll
;                 for (int bj = 0; bj < 2; ++bj) { const int col = col0 + bj * HALF;
;                     if (br < 2) {
;                         const u32x4 ga = *(const u32x4*)(hrow + C_GL + br * 1024 + col), gb = *(const u32x4*)(hrow + C_GL + (br + 1) * 1024 + col);
;                         float r[8];
; #pragma unroll
;                         for (int e = 0; e < 4; ++e) { const unsigned wa = ga[e], wb = gb[e];
;                             r[2 * e]     = bf_lo(wa) * __builtin_amdgcn_rcpf(bf_lo(wb));
;                             r[2 * e + 1] = bf_hi(wa) * __builtin_amdgcn_rcpf(bf_hi(wb)); }
;                         acc[ai][bj][m][0] *= (f32x4){r[0], r[1], r[2], r[3]}; acc[ai][bj][m][1] *= (f32x4){r[4], r[5], r[6], r[7]};
;                     } else {
;                         const u32x4 gc = *(const u32x4*)(hrow + C_GL + 2048 + col);
;                         f32x4 g0, g1;
;                         g0[0] = bf_lo(gc.x); g0[1] = bf_hi(gc.x); g0[2] = bf_lo(gc.y); g0[3] = bf_hi(gc.y);
;                         g1[0] = bf_lo(gc.z); g1[1] = bf_hi(gc.z); g1[2] = bf_lo(gc.w); g1[3] = bf_hi(gc.w);
;                         const f32x4 v0 = acc[ai][bj][m][0] * g0, v1 = acc[ai][bj][m][1] * g1;
;                         u32x4 w; w.x = cvt_pk_bf16(v0[0], v0[1]); w.y = cvt_pk_bf16(v0[2], v0[3]); w.z = cvt_pk_bf16(v1[0], v1[1]); w.w = cvt_pk_bf16(v1[2], v1[3]);
;                         *(u32x4*)(hrow + C_AZ + col) = w;
;                         acc[ai][bj][m][0] = (f32x4){0.f, 0.f, 0.f, 0.f}; acc[ai][bj][m][1] = (f32x4){0.f, 0.f, 0.f, 0.f};
;                     }
.LBB0_673:
	s_and_b64 vcc, exec, s[40:41]
	s_mov_b64 s[76:77], -1
	s_cbranch_vccnz .LBB0_675
	v_lshl_add_u64 v[106:107], v[116:117], 0, v[160:161]
	v_lshl_add_u64 v[110:111], v[114:115], 0, v[160:161]
	s_mov_b64 s[76:77], 0
	s_waitcnt vmcnt(14)
	v_mov_b32_e32 v106, v212
	v_mov_b32_e32 v107, v213
	v_mov_b32_e32 v108, v214
	v_mov_b32_e32 v109, v215
	global_load_dwordx4 v[212:215], v[186:187], off offset:256
	v_lshlrev_b32_e32 v112, 16, v106
	v_and_b32_e32 v113, 0xffff0000, v106
	v_lshlrev_b32_e32 v106, 16, v107
	v_and_b32_e32 v107, 0xffff0000, v107
	v_lshlrev_b32_e32 v114, 16, v108
	v_and_b32_e32 v115, 0xffff0000, v108
	v_lshlrev_b32_e32 v108, 16, v109
	v_and_b32_e32 v109, 0xffff0000, v109
	v_pk_mul_f32 v[116:117], v[104:105], v[106:107]
	v_pk_mul_f32 v[106:107], v[102:103], v[112:113]
	v_pk_mul_f32 v[112:113], v[100:101], v[108:109]
	v_pk_mul_f32 v[108:109], v[98:99], v[114:115]
	v_cvt_pk_bf16_f32 v106, v106, v107
	v_cvt_pk_bf16_f32 v107, v116, v117
	s_nop 0
	v_cvt_pk_bf16_f32 v108, v108, v109
	v_cvt_pk_bf16_f32 v109, v112, v113
	global_store_dwordx4 v[110:111], v[106:109], off
.LBB0_675:
	s_nop 1
	v_mov_b32_e32 v106, 0
	s_andn2_b64 vcc, exec, s[76:77]
	v_mov_b32_e32 v107, 0
	v_mov_b32_e32 v112, 0
	v_mov_b32_e32 v113, 0
	v_mov_b32_e32 v108, 0
	v_mov_b32_e32 v109, 0
	v_mov_b32_e32 v110, 0
	v_mov_b32_e32 v111, 0
	s_cbranch_vccnz .LBB0_677
	s_waitcnt vmcnt(10)
	v_mov_b32_e32 v106, v224
	v_mov_b32_e32 v107, v225
	v_mov_b32_e32 v108, v226
	v_mov_b32_e32 v109, v227
	v_mov_b32_e32 v110, v228
	v_mov_b32_e32 v111, v229
	v_mov_b32_e32 v112, v230
	v_mov_b32_e32 v113, v231
	global_load_dwordx4 v[224:227], v[186:187], off offset:256
	global_load_dwordx4 v[228:231], v[186:187], off offset:2304
	v_lshl_add_u64 v[186:187], v[186:187], 0, s[8:9]
	v_lshlrev_b32_e32 v116, 16, v106
	v_lshlrev_b32_e32 v114, 16, v110
	v_and_b32_e32 v110, 0xffff0000, v110
	v_and_b32_e32 v117, 0xffff0000, v106
	v_lshlrev_b32_e32 v106, 16, v111
	v_rcp_f32_e32 v115, v110
	v_rcp_f32_e32 v110, v106
	v_and_b32_e32 v106, 0xffff0000, v111
	v_rcp_f32_e32 v111, v106
	v_lshlrev_b32_e32 v106, 16, v107
	v_and_b32_e32 v107, 0xffff0000, v107
	v_rcp_f32_e32 v114, v114
	v_pk_mul_f32 v[106:107], v[110:111], v[106:107]
	v_lshlrev_b32_e32 v110, 16, v112
	v_and_b32_e32 v111, 0xffff0000, v112
	v_rcp_f32_e32 v110, v110
	v_rcp_f32_e32 v111, v111
	v_pk_mul_f32 v[114:115], v[114:115], v[116:117]
	v_lshlrev_b32_e32 v116, 16, v108
	v_and_b32_e32 v117, 0xffff0000, v108
	v_lshlrev_b32_e32 v108, 16, v113
	v_pk_mul_f32 v[116:117], v[110:111], v[116:117]
	v_rcp_f32_e32 v110, v108
	v_and_b32_e32 v108, 0xffff0000, v113
	v_rcp_f32_e32 v111, v108
	v_lshlrev_b32_e32 v108, 16, v109
	v_and_b32_e32 v109, 0xffff0000, v109
	v_pk_mul_f32 v[112:113], v[110:111], v[108:109]
	v_pk_mul_f32 v[110:111], v[104:105], v[106:107]
	v_pk_mul_f32 v[108:109], v[102:103], v[114:115]
	v_pk_mul_f32 v[112:113], v[100:101], v[112:113]
	v_pk_mul_f32 v[106:107], v[98:99], v[116:117]
.LBB0_677:
	v_or_b32_e32 v100, 32, v184
	v_mov_b64_e32 v[98:99], s[58:59]
	v_mad_i64_i32 v[102:103], s[4:5], v100, s18, v[98:99]
	v_lshl_add_u64 v[100:101], v[102:103], 0, s[52:53]
	v_lshl_add_u64 v[98:99], v[102:103], 0, s[54:55]
	s_and_b64 vcc, exec, s[40:41]
	s_mov_b64 s[76:77], -1
	s_cbranch_vccnz .LBB0_679
	v_lshl_add_u64 v[104:105], v[100:101], 0, v[158:159]
	s_mov_b64 s[76:77], 0
	s_waitcnt vmcnt(15)
	v_mov_b32_e32 v114, v216
	v_mov_b32_e32 v115, v217
	v_mov_b32_e32 v116, v218
	v_mov_b32_e32 v117, v219
	v_lshlrev_b32_e32 v104, 16, v114
	v_and_b32_e32 v105, 0xffff0000, v114
	v_lshlrev_b32_e32 v114, 16, v115
	v_and_b32_e32 v115, 0xffff0000, v115
	v_lshlrev_b32_e32 v118, 16, v116
	v_and_b32_e32 v119, 0xffff0000, v116
	v_lshlrev_b32_e32 v116, 16, v117
	v_and_b32_e32 v117, 0xffff0000, v117
	v_pk_mul_f32 v[104:105], v[92:93], v[104:105]
	v_pk_mul_f32 v[120:121], v[94:95], v[114:115]
	v_pk_mul_f32 v[162:163], v[90:91], v[116:117]
	v_pk_mul_f32 v[116:117], v[88:89], v[118:119]
	v_cvt_pk_bf16_f32 v114, v104, v105
	v_lshl_add_u64 v[104:105], v[98:99], 0, v[158:159]
	v_cvt_pk_bf16_f32 v115, v120, v121
	v_cvt_pk_bf16_f32 v116, v116, v117
	v_cvt_pk_bf16_f32 v117, v162, v163
	global_store_dwordx4 v[104:105], v[114:117], off
.LBB0_679:
	v_lshl_add_u64 v[102:103], s[34:35], 1, v[102:103]
	v_lshl_add_u64 v[102:103], v[102:103], 0, s[60:61]
	v_mov_b32_e32 v162, 0
	s_andn2_b64 vcc, exec, s[76:77]
	v_lshl_add_u64 v[102:103], v[156:157], 1, v[102:103]
	v_mov_b32_e32 v163, 0
	v_mov_b32_e32 v168, 0
	v_mov_b32_e32 v169, 0
	v_mov_b32_e32 v164, 0
	v_mov_b32_e32 v165, 0
	v_mov_b32_e32 v166, 0
	v_mov_b32_e32 v167, 0
	s_cbranch_vccnz .LBB0_681
	s_waitcnt vmcnt(10)
	v_mov_b32_e32 v114, v232
	v_mov_b32_e32 v115, v233
	v_mov_b32_e32 v116, v234
	v_mov_b32_e32 v117, v235
	v_mov_b32_e32 v118, v236
	v_mov_b32_e32 v119, v237
	v_mov_b32_e32 v120, v238
	v_mov_b32_e32 v121, v239
	global_load_dwordx4 v[232:235], v[186:187], off
	global_load_dwordx4 v[236:239], v[186:187], off offset:2048
	v_lshlrev_b32_e32 v162, 16, v114
	v_lshlrev_b32_e32 v104, 16, v118
	v_and_b32_e32 v105, 0xffff0000, v118
	v_and_b32_e32 v163, 0xffff0000, v114
	v_lshlrev_b32_e32 v114, 16, v119
	v_rcp_f32_e32 v104, v104
	v_rcp_f32_e32 v105, v105
	v_rcp_f32_e32 v118, v114
	v_and_b32_e32 v114, 0xffff0000, v119
	v_rcp_f32_e32 v119, v114
	v_pk_mul_f32 v[104:105], v[104:105], v[162:163]
	v_lshlrev_b32_e32 v114, 16, v115
	v_and_b32_e32 v115, 0xffff0000, v115
	v_lshlrev_b32_e32 v162, 16, v116
	v_and_b32_e32 v163, 0xffff0000, v116
	v_lshlrev_b32_e32 v116, 16, v121
	v_pk_mul_f32 v[114:115], v[118:119], v[114:115]
	v_lshlrev_b32_e32 v118, 16, v120
	v_and_b32_e32 v119, 0xffff0000, v120
	v_rcp_f32_e32 v120, v116
	v_and_b32_e32 v116, 0xffff0000, v121
	v_rcp_f32_e32 v118, v118
	v_rcp_f32_e32 v119, v119
	v_rcp_f32_e32 v121, v116
	v_lshlrev_b32_e32 v116, 16, v117
	v_and_b32_e32 v117, 0xffff0000, v117
	v_pk_mul_f32 v[118:119], v[118:119], v[162:163]
	v_pk_mul_f32 v[116:117], v[120:121], v[116:117]
	v_pk_mul_f32 v[166:167], v[94:95], v[114:115]
	v_pk_mul_f32 v[164:165], v[92:93], v[104:105]
	v_pk_mul_f32 v[168:169], v[90:91], v[116:117]
	v_pk_mul_f32 v[162:163], v[88:89], v[118:119]
; __device__ __forceinline__ unsigned cvt_pk_bf16(float lo, float hi) { unsigned r; asm volatile("v_cvt_pk_bf16_f32 %0, %1, %2" : "=v"(r) : "v"(lo), "v"(hi)); return r; }
; __device__ __forceinline__ float bf_lo(unsigned u) { return __uint_as_float(u << 16); }
; __device__ __forceinline__ float bf_hi(unsigned u) { return __uint_as_float(u & 0xffff0000u); }
;     __device__ __forceinline__ void operator()(f32x4 (&acc)[2][2][4][2], const Unit& u, int wr, int wc, int fr, int fq) const {
;     ...
;             for (int m = 0; m < 4; ++m) { bf16_t* hrow = H + (size_t)(row0 + ai * HALF + m * 16) * INC;
; #pragma unroll
;                 for (int bj = 0; bj < 2; ++bj) { const int col = col0 + bj * HALF;
;                     if (br < 2) {
;                         const u32x4 ga = *(const u32x4*)(hrow + C_GL + br * 1024 + col), gb = *(const u32x4*)(hrow + C_GL + (br + 1) * 1024 + col);
;                         float r[8];
; #pragma unroll
;                         for (int e = 0; e < 4; ++e) { const unsigned wa = ga[e], wb = gb[e];
;                             r[2 * e]     = bf_lo(wa) * __builtin_amdgcn_rcpf(bf_lo(wb));
;                             r[2 * e + 1] = bf_hi(wa) * __builtin_amdgcn_rcpf(bf_hi(wb)); }
;                         acc[ai][bj][m][0] *= (f32x4){r[0], r[1], r[2], r[3]}; acc[ai][bj][m][1] *= (f32x4){r[4], r[5], r[6], r[7]};
;                     } else {
;                         const u32x4 gc = *(const u32x4*)(hrow + C_GL + 2048 + col);
;                         f32x4 g0, g1;
;                         g0[0] = bf_lo(gc.x); g0[1] = bf_hi(gc.x); g0[2] = bf_lo(gc.y); g0[3] = bf_hi(gc.y);
;                         g1[0] = bf_lo(gc.z); g1[1] = bf_hi(gc.z); g1[2] = bf_lo(gc.w); g1[3] = bf_hi(gc.w);
;                         const f32x4 v0 = acc[ai][bj][m][0] * g0, v1 = acc[ai][bj][m][1] * g1;
;                         u32x4 w; w.x = cvt_pk_bf16(v0[0], v0[1]); w.y = cvt_pk_bf16(v0[2], v0[3]); w.z = cvt_pk_bf16(v1[0], v1[1]); w.w = cvt_pk_bf16(v1[2], v1[3]);
;                         *(u32x4*)(hrow + C_AZ + col) = w;
;                         acc[ai][bj][m][0] = (f32x4){0.f, 0.f, 0.f, 0.f}; acc[ai][bj][m][1] = (f32x4){0.f, 0.f, 0.f, 0.f};
;                     }
.LBB0_681:
	s_and_b64 vcc, exec, s[40:41]
	s_mov_b64 s[76:77], -1
	s_cbranch_vccnz .LBB0_683
	v_lshl_add_u64 v[88:89], v[100:101], 0, v[160:161]
	v_lshl_add_u64 v[92:93], v[98:99], 0, v[160:161]
	s_mov_b64 s[76:77], 0
	s_waitcnt vmcnt(15)
	v_mov_b32_e32 v88, v220
	v_mov_b32_e32 v89, v221
	v_mov_b32_e32 v90, v222
	v_mov_b32_e32 v91, v223
	v_lshlrev_b32_e32 v94, 16, v88
	v_and_b32_e32 v95, 0xffff0000, v88
	v_lshlrev_b32_e32 v88, 16, v89
	v_and_b32_e32 v89, 0xffff0000, v89
	v_lshlrev_b32_e32 v98, 16, v90
	v_and_b32_e32 v99, 0xffff0000, v90
	v_lshlrev_b32_e32 v90, 16, v91
	v_and_b32_e32 v91, 0xffff0000, v91
	v_pk_mul_f32 v[100:101], v[86:87], v[88:89]
	v_pk_mul_f32 v[88:89], v[84:85], v[94:95]
	v_pk_mul_f32 v[94:95], v[82:83], v[90:91]
	v_pk_mul_f32 v[90:91], v[80:81], v[98:99]
	v_cvt_pk_bf16_f32 v88, v88, v89
	v_cvt_pk_bf16_f32 v89, v100, v101
	s_nop 0
	v_cvt_pk_bf16_f32 v90, v90, v91
	v_cvt_pk_bf16_f32 v91, v94, v95
	global_store_dwordx4 v[92:93], v[88:91], off
.LBB0_683:
	s_nop 1
	v_mov_b32_e32 v88, 0
	s_andn2_b64 vcc, exec, s[76:77]
	v_mov_b32_e32 v89, 0
	v_mov_b32_e32 v94, 0
	v_mov_b32_e32 v95, 0
	v_mov_b32_e32 v90, 0
	v_mov_b32_e32 v91, 0
	v_mov_b32_e32 v92, 0
	v_mov_b32_e32 v93, 0
	s_cbranch_vccnz .LBB0_685
	s_waitcnt vmcnt(10)
	v_mov_b32_e32 v88, v240
	v_mov_b32_e32 v89, v241
	v_mov_b32_e32 v90, v242
	v_mov_b32_e32 v91, v243
	v_mov_b32_e32 v92, v244
	v_mov_b32_e32 v93, v245
	v_mov_b32_e32 v94, v246
	v_mov_b32_e32 v95, v247
	global_load_dwordx4 v[240:243], v[186:187], off offset:256
	global_load_dwordx4 v[244:247], v[186:187], off offset:2304
	v_lshl_add_u64 v[186:187], v[186:187], 0, s[8:9]
	v_lshlrev_b32_e32 v100, 16, v88
	v_lshlrev_b32_e32 v98, 16, v92
	v_and_b32_e32 v92, 0xffff0000, v92
	v_and_b32_e32 v101, 0xffff0000, v88
	v_lshlrev_b32_e32 v88, 16, v93
	v_rcp_f32_e32 v99, v92
	v_rcp_f32_e32 v92, v88
	v_and_b32_e32 v88, 0xffff0000, v93
	v_rcp_f32_e32 v93, v88
	v_lshlrev_b32_e32 v88, 16, v89
	v_and_b32_e32 v89, 0xffff0000, v89
	v_rcp_f32_e32 v98, v98
	v_pk_mul_f32 v[88:89], v[92:93], v[88:89]
	v_lshlrev_b32_e32 v92, 16, v94
	v_and_b32_e32 v93, 0xffff0000, v94
	v_rcp_f32_e32 v92, v92
	v_rcp_f32_e32 v93, v93
	v_pk_mul_f32 v[98:99], v[98:99], v[100:101]
	v_lshlrev_b32_e32 v100, 16, v90
	v_and_b32_e32 v101, 0xffff0000, v90
	v_lshlrev_b32_e32 v90, 16, v95
	v_pk_mul_f32 v[100:101], v[92:93], v[100:101]
	v_rcp_f32_e32 v92, v90
	v_and_b32_e32 v90, 0xffff0000, v95
	v_rcp_f32_e32 v93, v90
	v_lshlrev_b32_e32 v90, 16, v91
	v_and_b32_e32 v91, 0xffff0000, v91
	v_pk_mul_f32 v[94:95], v[92:93], v[90:91]
	v_pk_mul_f32 v[92:93], v[86:87], v[88:89]
	v_pk_mul_f32 v[90:91], v[84:85], v[98:99]
	v_pk_mul_f32 v[94:95], v[82:83], v[94:95]
	v_pk_mul_f32 v[88:89], v[80:81], v[100:101]
.LBB0_685:
	v_or_b32_e32 v82, 48, v184
	v_mov_b64_e32 v[80:81], s[58:59]
	v_mad_i64_i32 v[84:85], s[4:5], v82, s18, v[80:81]
	v_lshl_add_u64 v[82:83], v[84:85], 0, s[52:53]
	v_lshl_add_u64 v[80:81], v[84:85], 0, s[54:55]
	s_and_b64 vcc, exec, s[40:41]
	s_mov_b64 s[76:77], -1
	s_cbranch_vccnz .LBB0_687
	v_lshl_add_u64 v[86:87], v[82:83], 0, v[158:159]
	s_mov_b64 s[76:77], 0
	s_waitcnt vmcnt(15)
	v_mov_b32_e32 v98, v224
	v_mov_b32_e32 v99, v225
	v_mov_b32_e32 v100, v226
	v_mov_b32_e32 v101, v227
	v_lshlrev_b32_e32 v86, 16, v98
	v_and_b32_e32 v87, 0xffff0000, v98
	v_lshlrev_b32_e32 v98, 16, v99
	v_and_b32_e32 v99, 0xffff0000, v99
	v_lshlrev_b32_e32 v102, 16, v100
	v_and_b32_e32 v103, 0xffff0000, v100
	v_lshlrev_b32_e32 v100, 16, v101
	v_and_b32_e32 v101, 0xffff0000, v101
	v_pk_mul_f32 v[86:87], v[76:77], v[86:87]
	v_pk_mul_f32 v[104:105], v[78:79], v[98:99]
	v_pk_mul_f32 v[114:115], v[74:75], v[100:101]
	v_pk_mul_f32 v[100:101], v[72:73], v[102:103]
	v_cvt_pk_bf16_f32 v98, v86, v87
	v_lshl_add_u64 v[86:87], v[80:81], 0, v[158:159]
	v_cvt_pk_bf16_f32 v99, v104, v105
	v_cvt_pk_bf16_f32 v100, v100, v101
	v_cvt_pk_bf16_f32 v101, v114, v115
	global_store_dwordx4 v[86:87], v[98:101], off
.LBB0_687:
	v_lshl_add_u64 v[84:85], s[34:35], 1, v[84:85]
	v_lshl_add_u64 v[84:85], v[84:85], 0, s[60:61]
	v_mov_b32_e32 v170, 0
	s_andn2_b64 vcc, exec, s[76:77]
	v_lshl_add_u64 v[84:85], v[156:157], 1, v[84:85]
	v_mov_b32_e32 v171, 0
	v_mov_b32_e32 v176, 0
	v_mov_b32_e32 v177, 0
	v_mov_b32_e32 v172, 0
	v_mov_b32_e32 v173, 0
	v_mov_b32_e32 v174, 0
	v_mov_b32_e32 v175, 0
	s_cbranch_vccnz .LBB0_689
	s_waitcnt vmcnt(10)
	v_mov_b32_e32 v98, v188
	v_mov_b32_e32 v99, v189
	v_mov_b32_e32 v100, v190
	v_mov_b32_e32 v101, v191
	v_mov_b32_e32 v102, v192
	v_mov_b32_e32 v103, v193
	v_mov_b32_e32 v104, v194
	v_mov_b32_e32 v105, v195
	global_load_dwordx4 v[188:191], v[186:187], off
	global_load_dwordx4 v[192:195], v[186:187], off offset:2048
	v_lshlrev_b32_e32 v114, 16, v98
	v_lshlrev_b32_e32 v86, 16, v102
	v_and_b32_e32 v87, 0xffff0000, v102
	v_and_b32_e32 v115, 0xffff0000, v98
	v_lshlrev_b32_e32 v98, 16, v103
	v_rcp_f32_e32 v86, v86
	v_rcp_f32_e32 v87, v87
	v_rcp_f32_e32 v102, v98
	v_and_b32_e32 v98, 0xffff0000, v103
	v_rcp_f32_e32 v103, v98
	v_pk_mul_f32 v[86:87], v[86:87], v[114:115]
	v_lshlrev_b32_e32 v98, 16, v99
	v_and_b32_e32 v99, 0xffff0000, v99
	v_lshlrev_b32_e32 v114, 16, v100
	v_and_b32_e32 v115, 0xffff0000, v100
	v_lshlrev_b32_e32 v100, 16, v105
	v_pk_mul_f32 v[98:99], v[102:103], v[98:99]
	v_lshlrev_b32_e32 v102, 16, v104
	v_and_b32_e32 v103, 0xffff0000, v104
	v_rcp_f32_e32 v104, v100
	v_and_b32_e32 v100, 0xffff0000, v105
	v_rcp_f32_e32 v102, v102
	v_rcp_f32_e32 v103, v103
	v_rcp_f32_e32 v105, v100
	v_lshlrev_b32_e32 v100, 16, v101
	v_and_b32_e32 v101, 0xffff0000, v101
	v_pk_mul_f32 v[102:103], v[102:103], v[114:115]
	v_pk_mul_f32 v[100:101], v[104:105], v[100:101]
	v_pk_mul_f32 v[174:175], v[78:79], v[98:99]
	v_pk_mul_f32 v[172:173], v[76:77], v[86:87]
	v_pk_mul_f32 v[176:177], v[74:75], v[100:101]
	v_pk_mul_f32 v[170:171], v[72:73], v[102:103]
; __device__ __forceinline__ unsigned cvt_pk_bf16(float lo, float hi) { unsigned r; asm volatile("v_cvt_pk_bf16_f32 %0, %1, %2" : "=v"(r) : "v"(lo), "v"(hi)); return r; }
; __device__ __forceinline__ float bf_lo(unsigned u) { return __uint_as_float(u << 16); }
; __device__ __forceinline__ float bf_hi(unsigned u) { return __uint_as_float(u & 0xffff0000u); }
;     __device__ __forceinline__ void operator()(f32x4 (&acc)[2][2][4][2], const Unit& u, int wr, int wc, int fr, int fq) const {
;     ...
;             for (int m = 0; m < 4; ++m) { bf16_t* hrow = H + (size_t)(row0 + ai * HALF + m * 16) * INC;
; #pragma unroll
;                 for (int bj = 0; bj < 2; ++bj) { const int col = col0 + bj * HALF;
;                     if (br < 2) {
;                         const u32x4 ga = *(const u32x4*)(hrow + C_GL + br * 1024 + col), gb = *(const u32x4*)(hrow + C_GL + (br + 1) * 1024 + col);
;                         float r[8];
; #pragma unroll
;                         for (int e = 0; e < 4; ++e) { const unsigned wa = ga[e], wb = gb[e];
;                             r[2 * e]     = bf_lo(wa) * __builtin_amdgcn_rcpf(bf_lo(wb));
;                             r[2 * e + 1] = bf_hi(wa) * __builtin_amdgcn_rcpf(bf_hi(wb)); }
;                         acc[ai][bj][m][0] *= (f32x4){r[0], r[1], r[2], r[3]}; acc[ai][bj][m][1] *= (f32x4){r[4], r[5], r[6], r[7]};
;                     } else {
;                         const u32x4 gc = *(const u32x4*)(hrow + C_GL + 2048 + col);
;                         f32x4 g0, g1;
;                         g0[0] = bf_lo(gc.x); g0[1] = bf_hi(gc.x); g0[2] = bf_lo(gc.y); g0[3] = bf_hi(gc.y);
;                         g1[0] = bf_lo(gc.z); g1[1] = bf_hi(gc.z); g1[2] = bf_lo(gc.w); g1[3] = bf_hi(gc.w);
;                         const f32x4 v0 = acc[ai][bj][m][0] * g0, v1 = acc[ai][bj][m][1] * g1;
;                         u32x4 w; w.x = cvt_pk_bf16(v0[0], v0[1]); w.y = cvt_pk_bf16(v0[2], v0[3]); w.z = cvt_pk_bf16(v1[0], v1[1]); w.w = cvt_pk_bf16(v1[2], v1[3]);
;                         *(u32x4*)(hrow + C_AZ + col) = w;
;                         acc[ai][bj][m][0] = (f32x4){0.f, 0.f, 0.f, 0.f}; acc[ai][bj][m][1] = (f32x4){0.f, 0.f, 0.f, 0.f};
;                     }
.LBB0_689:
	s_and_b64 vcc, exec, s[40:41]
	s_mov_b64 s[76:77], -1
	s_cbranch_vccnz .LBB0_691
	v_lshl_add_u64 v[72:73], v[82:83], 0, v[160:161]
	v_lshl_add_u64 v[76:77], v[80:81], 0, v[160:161]
	s_mov_b64 s[76:77], 0
	s_waitcnt vmcnt(15)
	v_mov_b32_e32 v72, v228
	v_mov_b32_e32 v73, v229
	v_mov_b32_e32 v74, v230
	v_mov_b32_e32 v75, v231
	v_lshlrev_b32_e32 v78, 16, v72
	v_and_b32_e32 v79, 0xffff0000, v72
	v_lshlrev_b32_e32 v72, 16, v73
	v_and_b32_e32 v73, 0xffff0000, v73
	v_lshlrev_b32_e32 v80, 16, v74
	v_and_b32_e32 v81, 0xffff0000, v74
	v_lshlrev_b32_e32 v74, 16, v75
	v_and_b32_e32 v75, 0xffff0000, v75
	v_pk_mul_f32 v[82:83], v[70:71], v[72:73]
	v_pk_mul_f32 v[72:73], v[68:69], v[78:79]
	v_pk_mul_f32 v[78:79], v[66:67], v[74:75]
	v_pk_mul_f32 v[74:75], v[64:65], v[80:81]
	v_cvt_pk_bf16_f32 v72, v72, v73
	v_cvt_pk_bf16_f32 v73, v82, v83
	s_nop 0
	v_cvt_pk_bf16_f32 v74, v74, v75
	v_cvt_pk_bf16_f32 v75, v78, v79
	global_store_dwordx4 v[76:77], v[72:75], off
.LBB0_691:
	s_nop 1
	v_mov_b32_e32 v72, 0
	s_andn2_b64 vcc, exec, s[76:77]
	v_mov_b32_e32 v73, 0
	v_mov_b32_e32 v78, 0
	v_mov_b32_e32 v79, 0
	v_mov_b32_e32 v74, 0
	v_mov_b32_e32 v75, 0
	v_mov_b32_e32 v76, 0
	v_mov_b32_e32 v77, 0
	s_cbranch_vccnz .LBB0_693
	s_waitcnt vmcnt(10)
	v_mov_b32_e32 v72, v196
	v_mov_b32_e32 v73, v197
	v_mov_b32_e32 v74, v198
	v_mov_b32_e32 v75, v199
	v_mov_b32_e32 v76, v212
	v_mov_b32_e32 v77, v213
	v_mov_b32_e32 v78, v214
	v_mov_b32_e32 v79, v215
	global_load_dwordx4 v[196:199], v[186:187], off offset:256
	global_load_dwordx4 v[212:215], v[186:187], off offset:2304
	v_lshl_add_u64 v[186:187], v[186:187], 0, s[8:9]
	v_lshlrev_b32_e32 v82, 16, v72
	v_lshlrev_b32_e32 v80, 16, v76
	v_and_b32_e32 v76, 0xffff0000, v76
	v_and_b32_e32 v83, 0xffff0000, v72
	v_lshlrev_b32_e32 v72, 16, v77
	v_rcp_f32_e32 v81, v76
	v_rcp_f32_e32 v76, v72
	v_and_b32_e32 v72, 0xffff0000, v77
	v_rcp_f32_e32 v77, v72
	v_lshlrev_b32_e32 v72, 16, v73
	v_and_b32_e32 v73, 0xffff0000, v73
	v_rcp_f32_e32 v80, v80
	v_pk_mul_f32 v[72:73], v[76:77], v[72:73]
	v_lshlrev_b32_e32 v76, 16, v78
	v_and_b32_e32 v77, 0xffff0000, v78
	v_rcp_f32_e32 v76, v76
	v_rcp_f32_e32 v77, v77
	v_pk_mul_f32 v[80:81], v[80:81], v[82:83]
	v_lshlrev_b32_e32 v82, 16, v74
	v_and_b32_e32 v83, 0xffff0000, v74
	v_lshlrev_b32_e32 v74, 16, v79
	v_pk_mul_f32 v[82:83], v[76:77], v[82:83]
	v_rcp_f32_e32 v76, v74
	v_and_b32_e32 v74, 0xffff0000, v79
	v_rcp_f32_e32 v77, v74
	v_lshlrev_b32_e32 v74, 16, v75
	v_and_b32_e32 v75, 0xffff0000, v75
	v_pk_mul_f32 v[78:79], v[76:77], v[74:75]
	v_pk_mul_f32 v[76:77], v[70:71], v[72:73]
	v_pk_mul_f32 v[74:75], v[68:69], v[80:81]
	v_pk_mul_f32 v[78:79], v[66:67], v[78:79]
	v_pk_mul_f32 v[72:73], v[64:65], v[82:83]
.LBB0_693:
	v_add_u32_e32 v66, 0x80, v184
	v_mov_b64_e32 v[64:65], s[58:59]
	v_mad_i64_i32 v[64:65], s[4:5], v66, s18, v[64:65]
	v_lshl_add_u64 v[82:83], v[64:65], 0, s[52:53]
	v_lshl_add_u64 v[80:81], v[64:65], 0, s[54:55]
	s_and_b64 vcc, exec, s[40:41]
	s_mov_b64 s[76:77], -1
	s_cbranch_vccnz .LBB0_695
	v_lshl_add_u64 v[66:67], v[82:83], 0, v[158:159]
	s_mov_b64 s[76:77], 0
	s_waitcnt vmcnt(15)
	v_mov_b32_e32 v66, v232
	v_mov_b32_e32 v67, v233
	v_mov_b32_e32 v68, v234
	v_mov_b32_e32 v69, v235
	v_lshlrev_b32_e32 v70, 16, v66
	v_and_b32_e32 v71, 0xffff0000, v66
	v_lshlrev_b32_e32 v66, 16, v67
	v_and_b32_e32 v67, 0xffff0000, v67
	v_lshlrev_b32_e32 v84, 16, v68
	v_and_b32_e32 v85, 0xffff0000, v68
	v_lshlrev_b32_e32 v68, 16, v69
	v_and_b32_e32 v69, 0xffff0000, v69
	v_pk_mul_f32 v[86:87], v[62:63], v[66:67]
	v_pk_mul_f32 v[66:67], v[60:61], v[70:71]
	v_pk_mul_f32 v[70:71], v[58:59], v[68:69]
	v_pk_mul_f32 v[68:69], v[56:57], v[84:85]
	v_cvt_pk_bf16_f32 v66, v66, v67
	v_cvt_pk_bf16_f32 v67, v86, v87
	s_nop 0
	v_cvt_pk_bf16_f32 v68, v68, v69
	v_cvt_pk_bf16_f32 v69, v70, v71
	v_lshl_add_u64 v[70:71], v[80:81], 0, v[158:159]
	global_store_dwordx4 v[70:71], v[66:69], off
.LBB0_695:
	v_lshl_add_u64 v[64:65], s[34:35], 1, v[64:65]
	s_nop 0
	v_lshl_add_u64 v[66:67], v[64:65], 0, s[60:61]
	v_mov_b32_e32 v64, 0
	s_andn2_b64 vcc, exec, s[76:77]
	v_lshl_add_u64 v[84:85], v[156:157], 1, v[66:67]
	v_mov_b32_e32 v65, 0
	v_mov_b32_e32 v70, 0
	v_mov_b32_e32 v71, 0
	v_mov_b32_e32 v66, 0
	v_mov_b32_e32 v67, 0
	v_mov_b32_e32 v68, 0
	v_mov_b32_e32 v69, 0
	s_cbranch_vccnz .LBB0_697
	s_waitcnt vmcnt(10)
	v_mov_b32_e32 v64, v216
	v_mov_b32_e32 v65, v217
	v_mov_b32_e32 v66, v218
	v_mov_b32_e32 v67, v219
	v_mov_b32_e32 v68, v220
	v_mov_b32_e32 v69, v221
	v_mov_b32_e32 v70, v222
	v_mov_b32_e32 v71, v223
	global_load_dwordx4 v[216:219], v[186:187], off
	global_load_dwordx4 v[220:223], v[186:187], off offset:2048
	v_lshlrev_b32_e32 v98, 16, v64
	v_lshlrev_b32_e32 v86, 16, v68
	v_and_b32_e32 v68, 0xffff0000, v68
	v_and_b32_e32 v99, 0xffff0000, v64
	v_lshlrev_b32_e32 v64, 16, v69
	v_rcp_f32_e32 v87, v68
	v_rcp_f32_e32 v68, v64
	v_and_b32_e32 v64, 0xffff0000, v69
	v_rcp_f32_e32 v69, v64
	v_lshlrev_b32_e32 v64, 16, v65
	v_and_b32_e32 v65, 0xffff0000, v65
	v_rcp_f32_e32 v86, v86
	v_pk_mul_f32 v[64:65], v[68:69], v[64:65]
	v_lshlrev_b32_e32 v68, 16, v70
	v_and_b32_e32 v69, 0xffff0000, v70
	v_rcp_f32_e32 v68, v68
	v_rcp_f32_e32 v69, v69
	v_pk_mul_f32 v[86:87], v[86:87], v[98:99]
	v_lshlrev_b32_e32 v98, 16, v66
	v_and_b32_e32 v99, 0xffff0000, v66
	v_lshlrev_b32_e32 v66, 16, v71
	v_pk_mul_f32 v[98:99], v[68:69], v[98:99]
	v_rcp_f32_e32 v68, v66
	v_and_b32_e32 v66, 0xffff0000, v71
	v_rcp_f32_e32 v69, v66
	v_lshlrev_b32_e32 v66, 16, v67
	v_and_b32_e32 v67, 0xffff0000, v67
	v_pk_mul_f32 v[70:71], v[68:69], v[66:67]
	v_pk_mul_f32 v[68:69], v[62:63], v[64:65]
	v_pk_mul_f32 v[66:67], v[60:61], v[86:87]
	v_pk_mul_f32 v[70:71], v[58:59], v[70:71]
	v_pk_mul_f32 v[64:65], v[56:57], v[98:99]
; __device__ __forceinline__ unsigned cvt_pk_bf16(float lo, float hi) { unsigned r; asm volatile("v_cvt_pk_bf16_f32 %0, %1, %2" : "=v"(r) : "v"(lo), "v"(hi)); return r; }
; __device__ __forceinline__ float bf_lo(unsigned u) { return __uint_as_float(u << 16); }
; __device__ __forceinline__ float bf_hi(unsigned u) { return __uint_as_float(u & 0xffff0000u); }
;     __device__ __forceinline__ void operator()(f32x4 (&acc)[2][2][4][2], const Unit& u, int wr, int wc, int fr, int fq) const {
;     ...
;             for (int m = 0; m < 4; ++m) { bf16_t* hrow = H + (size_t)(row0 + ai * HALF + m * 16) * INC;
; #pragma unroll
;                 for (int bj = 0; bj < 2; ++bj) { const int col = col0 + bj * HALF;
;                     if (br < 2) {
;                         const u32x4 ga = *(const u32x4*)(hrow + C_GL + br * 1024 + col), gb = *(const u32x4*)(hrow + C_GL + (br + 1) * 1024 + col);
;                         float r[8];
; #pragma unroll
;                         for (int e = 0; e < 4; ++e) { const unsigned wa = ga[e], wb = gb[e];
;                             r[2 * e]     = bf_lo(wa) * __builtin_amdgcn_rcpf(bf_lo(wb));
;                             r[2 * e + 1] = bf_hi(wa) * __builtin_amdgcn_rcpf(bf_hi(wb)); }
;                         acc[ai][bj][m][0] *= (f32x4){r[0], r[1], r[2], r[3]}; acc[ai][bj][m][1] *= (f32x4){r[4], r[5], r[6], r[7]};
;                     } else {
;                         const u32x4 gc = *(const u32x4*)(hrow + C_GL + 2048 + col);
;                         f32x4 g0, g1;
;                         g0[0] = bf_lo(gc.x); g0[1] = bf_hi(gc.x); g0[2] = bf_lo(gc.y); g0[3] = bf_hi(gc.y);
;                         g1[0] = bf_lo(gc.z); g1[1] = bf_hi(gc.z); g1[2] = bf_lo(gc.w); g1[3] = bf_hi(gc.w);
;                         const f32x4 v0 = acc[ai][bj][m][0] * g0, v1 = acc[ai][bj][m][1] * g1;
;                         u32x4 w; w.x = cvt_pk_bf16(v0[0], v0[1]); w.y = cvt_pk_bf16(v0[2], v0[3]); w.z = cvt_pk_bf16(v1[0], v1[1]); w.w = cvt_pk_bf16(v1[2], v1[3]);
;                         *(u32x4*)(hrow + C_AZ + col) = w;
;                         acc[ai][bj][m][0] = (f32x4){0.f, 0.f, 0.f, 0.f}; acc[ai][bj][m][1] = (f32x4){0.f, 0.f, 0.f, 0.f};
;                     }
.LBB0_697:
	s_and_b64 vcc, exec, s[40:41]
	s_mov_b64 s[76:77], -1
	s_cbranch_vccnz .LBB0_699
	v_lshl_add_u64 v[56:57], v[82:83], 0, v[160:161]
	v_lshl_add_u64 v[60:61], v[80:81], 0, v[160:161]
	s_mov_b64 s[76:77], 0
	s_waitcnt vmcnt(15)
	v_mov_b32_e32 v56, v236
	v_mov_b32_e32 v57, v237
	v_mov_b32_e32 v58, v238
	v_mov_b32_e32 v59, v239
	v_lshlrev_b32_e32 v62, 16, v56
	v_and_b32_e32 v63, 0xffff0000, v56
	v_lshlrev_b32_e32 v56, 16, v57
	v_and_b32_e32 v57, 0xffff0000, v57
	v_lshlrev_b32_e32 v80, 16, v58
	v_and_b32_e32 v81, 0xffff0000, v58
	v_lshlrev_b32_e32 v58, 16, v59
	v_and_b32_e32 v59, 0xffff0000, v59
	v_pk_mul_f32 v[82:83], v[54:55], v[56:57]
	v_pk_mul_f32 v[56:57], v[52:53], v[62:63]
	v_pk_mul_f32 v[62:63], v[50:51], v[58:59]
	v_pk_mul_f32 v[58:59], v[48:49], v[80:81]
	v_cvt_pk_bf16_f32 v56, v56, v57
	v_cvt_pk_bf16_f32 v57, v82, v83
	s_nop 0
	v_cvt_pk_bf16_f32 v58, v58, v59
	v_cvt_pk_bf16_f32 v59, v62, v63
	global_store_dwordx4 v[60:61], v[56:59], off
.LBB0_699:
	s_nop 1
	v_mov_b32_e32 v56, 0
	s_andn2_b64 vcc, exec, s[76:77]
	v_mov_b32_e32 v57, 0
	v_mov_b32_e32 v62, 0
	v_mov_b32_e32 v63, 0
	v_mov_b32_e32 v58, 0
	v_mov_b32_e32 v59, 0
	v_mov_b32_e32 v60, 0
	v_mov_b32_e32 v61, 0
	s_cbranch_vccnz .LBB0_701
	s_waitcnt vmcnt(10)
	v_mov_b32_e32 v56, v224
	v_mov_b32_e32 v57, v225
	v_mov_b32_e32 v58, v226
	v_mov_b32_e32 v59, v227
	v_mov_b32_e32 v60, v228
	v_mov_b32_e32 v61, v229
	v_mov_b32_e32 v62, v230
	v_mov_b32_e32 v63, v231
	global_load_dwordx4 v[224:227], v[186:187], off offset:256
	global_load_dwordx4 v[228:231], v[186:187], off offset:2304
	v_lshlrev_b32_e32 v82, 16, v56
	v_lshlrev_b32_e32 v80, 16, v60
	v_and_b32_e32 v60, 0xffff0000, v60
	v_and_b32_e32 v83, 0xffff0000, v56
	v_lshlrev_b32_e32 v56, 16, v61
	v_rcp_f32_e32 v81, v60
	v_rcp_f32_e32 v60, v56
	v_and_b32_e32 v56, 0xffff0000, v61
	v_rcp_f32_e32 v61, v56
	v_lshlrev_b32_e32 v56, 16, v57
	v_and_b32_e32 v57, 0xffff0000, v57
	v_rcp_f32_e32 v80, v80
	v_pk_mul_f32 v[56:57], v[60:61], v[56:57]
	v_lshlrev_b32_e32 v60, 16, v62
	v_and_b32_e32 v61, 0xffff0000, v62
	v_rcp_f32_e32 v60, v60
	v_rcp_f32_e32 v61, v61
	v_pk_mul_f32 v[80:81], v[80:81], v[82:83]
	v_lshlrev_b32_e32 v82, 16, v58
	v_and_b32_e32 v83, 0xffff0000, v58
	v_lshlrev_b32_e32 v58, 16, v63
	v_pk_mul_f32 v[82:83], v[60:61], v[82:83]
	v_rcp_f32_e32 v60, v58
	v_and_b32_e32 v58, 0xffff0000, v63
	v_rcp_f32_e32 v61, v58
	v_lshlrev_b32_e32 v58, 16, v59
	v_and_b32_e32 v59, 0xffff0000, v59
	v_pk_mul_f32 v[62:63], v[60:61], v[58:59]
	v_pk_mul_f32 v[60:61], v[54:55], v[56:57]
	v_pk_mul_f32 v[58:59], v[52:53], v[80:81]
	v_pk_mul_f32 v[62:63], v[50:51], v[62:63]
	v_pk_mul_f32 v[56:57], v[48:49], v[82:83]
.LBB0_701:
	v_add_u32_e32 v50, 0x90, v184
	v_mov_b64_e32 v[48:49], s[58:59]
	v_mad_i64_i32 v[52:53], s[4:5], v50, s18, v[48:49]
	v_lshl_add_u64 v[50:51], v[52:53], 0, s[52:53]
	v_lshl_add_u64 v[48:49], v[52:53], 0, s[54:55]
	s_and_b64 vcc, exec, s[40:41]
	s_mov_b64 s[76:77], -1
	s_cbranch_vccnz .LBB0_703
	v_lshl_add_u64 v[54:55], v[50:51], 0, v[158:159]
	s_mov_b64 s[76:77], 0
	s_waitcnt vmcnt(15)
	v_mov_b32_e32 v80, v240
	v_mov_b32_e32 v81, v241
	v_mov_b32_e32 v82, v242
	v_mov_b32_e32 v83, v243
	v_lshlrev_b32_e32 v54, 16, v80
	v_and_b32_e32 v55, 0xffff0000, v80
	v_lshlrev_b32_e32 v80, 16, v81
	v_and_b32_e32 v81, 0xffff0000, v81
	v_lshlrev_b32_e32 v84, 16, v82
	v_and_b32_e32 v85, 0xffff0000, v82
	v_lshlrev_b32_e32 v82, 16, v83
	v_and_b32_e32 v83, 0xffff0000, v83
	v_pk_mul_f32 v[54:55], v[44:45], v[54:55]
	v_pk_mul_f32 v[86:87], v[46:47], v[80:81]
	v_pk_mul_f32 v[98:99], v[42:43], v[82:83]
	v_pk_mul_f32 v[82:83], v[40:41], v[84:85]
	v_cvt_pk_bf16_f32 v80, v54, v55
	v_lshl_add_u64 v[54:55], v[48:49], 0, v[158:159]
	v_cvt_pk_bf16_f32 v81, v86, v87
	v_cvt_pk_bf16_f32 v82, v82, v83
	v_cvt_pk_bf16_f32 v83, v98, v99
	global_store_dwordx4 v[54:55], v[80:83], off
.LBB0_703:
	v_lshl_add_u64 v[52:53], s[34:35], 1, v[52:53]
	v_lshl_add_u64 v[52:53], v[52:53], 0, s[60:61]
	v_mov_b32_e32 v80, 0
	s_andn2_b64 vcc, exec, s[76:77]
	v_lshl_add_u64 v[52:53], v[156:157], 1, v[52:53]
	v_mov_b32_e32 v81, 0
	v_mov_b32_e32 v86, 0
	v_mov_b32_e32 v87, 0
	v_mov_b32_e32 v82, 0
	v_mov_b32_e32 v83, 0
	v_mov_b32_e32 v84, 0
	v_mov_b32_e32 v85, 0
	s_cbranch_vccnz .LBB0_705
	s_waitcnt vmcnt(10)
	v_mov_b32_e32 v80, v232
	v_mov_b32_e32 v81, v233
	v_mov_b32_e32 v82, v234
	v_mov_b32_e32 v83, v235
	v_mov_b32_e32 v84, v236
	v_mov_b32_e32 v85, v237
	v_mov_b32_e32 v86, v238
	v_mov_b32_e32 v87, v239
	v_lshlrev_b32_e32 v98, 16, v80
	v_and_b32_e32 v99, 0xffff0000, v80
	v_lshlrev_b32_e32 v80, 16, v85
	v_lshlrev_b32_e32 v54, 16, v84
	v_and_b32_e32 v55, 0xffff0000, v84
	v_rcp_f32_e32 v84, v80
	v_and_b32_e32 v80, 0xffff0000, v85
	v_rcp_f32_e32 v85, v80
	v_lshlrev_b32_e32 v80, 16, v81
	v_and_b32_e32 v81, 0xffff0000, v81
	v_rcp_f32_e32 v54, v54
	v_rcp_f32_e32 v55, v55
	v_pk_mul_f32 v[80:81], v[84:85], v[80:81]
	v_lshlrev_b32_e32 v84, 16, v86
	v_and_b32_e32 v85, 0xffff0000, v86
	v_rcp_f32_e32 v84, v84
	v_rcp_f32_e32 v85, v85
	v_pk_mul_f32 v[54:55], v[54:55], v[98:99]
	v_lshlrev_b32_e32 v98, 16, v82
	v_and_b32_e32 v99, 0xffff0000, v82
	v_lshlrev_b32_e32 v82, 16, v87
	v_pk_mul_f32 v[98:99], v[84:85], v[98:99]
	v_rcp_f32_e32 v84, v82
	v_and_b32_e32 v82, 0xffff0000, v87
	v_rcp_f32_e32 v85, v82
	v_lshlrev_b32_e32 v82, 16, v83
	v_and_b32_e32 v83, 0xffff0000, v83
	v_pk_mul_f32 v[86:87], v[84:85], v[82:83]
	v_pk_mul_f32 v[84:85], v[46:47], v[80:81]
	v_pk_mul_f32 v[82:83], v[44:45], v[54:55]
	v_pk_mul_f32 v[86:87], v[42:43], v[86:87]
	v_pk_mul_f32 v[80:81], v[40:41], v[98:99]
; __device__ __forceinline__ unsigned cvt_pk_bf16(float lo, float hi) { unsigned r; asm volatile("v_cvt_pk_bf16_f32 %0, %1, %2" : "=v"(r) : "v"(lo), "v"(hi)); return r; }
; __device__ __forceinline__ float bf_lo(unsigned u) { return __uint_as_float(u << 16); }
; __device__ __forceinline__ float bf_hi(unsigned u) { return __uint_as_float(u & 0xffff0000u); }
;     __device__ __forceinline__ void operator()(f32x4 (&acc)[2][2][4][2], const Unit& u, int wr, int wc, int fr, int fq) const {
;     ...
;             for (int m = 0; m < 4; ++m) { bf16_t* hrow = H + (size_t)(row0 + ai * HALF + m * 16) * INC;
; #pragma unroll
;                 for (int bj = 0; bj < 2; ++bj) { const int col = col0 + bj * HALF;
;                     if (br < 2) {
;                         const u32x4 ga = *(const u32x4*)(hrow + C_GL + br * 1024 + col), gb = *(const u32x4*)(hrow + C_GL + (br + 1) * 1024 + col);
;                         float r[8];
; #pragma unroll
;                         for (int e = 0; e < 4; ++e) { const unsigned wa = ga[e], wb = gb[e];
;                             r[2 * e]     = bf_lo(wa) * __builtin_amdgcn_rcpf(bf_lo(wb));
;                             r[2 * e + 1] = bf_hi(wa) * __builtin_amdgcn_rcpf(bf_hi(wb)); }
;                         acc[ai][bj][m][0] *= (f32x4){r[0], r[1], r[2], r[3]}; acc[ai][bj][m][1] *= (f32x4){r[4], r[5], r[6], r[7]};
;                     } else {
;                         const u32x4 gc = *(const u32x4*)(hrow + C_GL + 2048 + col);
;                         f32x4 g0, g1;
;                         g0[0] = bf_lo(gc.x); g0[1] = bf_hi(gc.x); g0[2] = bf_lo(gc.y); g0[3] = bf_hi(gc.y);
;                         g1[0] = bf_lo(gc.z); g1[1] = bf_hi(gc.z); g1[2] = bf_lo(gc.w); g1[3] = bf_hi(gc.w);
;                         const f32x4 v0 = acc[ai][bj][m][0] * g0, v1 = acc[ai][bj][m][1] * g1;
;                         u32x4 w; w.x = cvt_pk_bf16(v0[0], v0[1]); w.y = cvt_pk_bf16(v0[2], v0[3]); w.z = cvt_pk_bf16(v1[0], v1[1]); w.w = cvt_pk_bf16(v1[2], v1[3]);
;                         *(u32x4*)(hrow + C_AZ + col) = w;
;                         acc[ai][bj][m][0] = (f32x4){0.f, 0.f, 0.f, 0.f}; acc[ai][bj][m][1] = (f32x4){0.f, 0.f, 0.f, 0.f};
;                     }
.LBB0_705:
	s_and_b64 vcc, exec, s[40:41]
	s_mov_b64 s[76:77], -1
	s_cbranch_vccnz .LBB0_707
	v_lshl_add_u64 v[40:41], v[50:51], 0, v[160:161]
	v_lshl_add_u64 v[44:45], v[48:49], 0, v[160:161]
	s_mov_b64 s[76:77], 0
	s_waitcnt vmcnt(15)
	v_mov_b32_e32 v40, v244
	v_mov_b32_e32 v41, v245
	v_mov_b32_e32 v42, v246
	v_mov_b32_e32 v43, v247
	v_lshlrev_b32_e32 v46, 16, v40
	v_and_b32_e32 v47, 0xffff0000, v40
	v_lshlrev_b32_e32 v40, 16, v41
	v_and_b32_e32 v41, 0xffff0000, v41
	v_lshlrev_b32_e32 v48, 16, v42
	v_and_b32_e32 v49, 0xffff0000, v42
	v_lshlrev_b32_e32 v42, 16, v43
	v_and_b32_e32 v43, 0xffff0000, v43
	v_pk_mul_f32 v[50:51], v[38:39], v[40:41]
	v_pk_mul_f32 v[40:41], v[36:37], v[46:47]
	v_pk_mul_f32 v[46:47], v[34:35], v[42:43]
	v_pk_mul_f32 v[42:43], v[32:33], v[48:49]
	v_cvt_pk_bf16_f32 v40, v40, v41
	v_cvt_pk_bf16_f32 v41, v50, v51
	s_nop 0
	v_cvt_pk_bf16_f32 v42, v42, v43
	v_cvt_pk_bf16_f32 v43, v46, v47
	global_store_dwordx4 v[44:45], v[40:43], off
.LBB0_707:
	s_nop 1
	v_mov_b32_e32 v40, 0
	s_andn2_b64 vcc, exec, s[76:77]
	v_mov_b32_e32 v41, 0
	v_mov_b32_e32 v46, 0
	v_mov_b32_e32 v47, 0
	v_mov_b32_e32 v42, 0
	v_mov_b32_e32 v43, 0
	v_mov_b32_e32 v44, 0
	v_mov_b32_e32 v45, 0
	s_cbranch_vccnz .LBB0_709
	s_waitcnt vmcnt(8)
	v_mov_b32_e32 v40, v240
	v_mov_b32_e32 v41, v241
	v_mov_b32_e32 v42, v242
	v_mov_b32_e32 v43, v243
	v_mov_b32_e32 v44, v244
	v_mov_b32_e32 v45, v245
	v_mov_b32_e32 v46, v246
	v_mov_b32_e32 v47, v247
	v_lshlrev_b32_e32 v50, 16, v40
	v_lshlrev_b32_e32 v48, 16, v44
	v_and_b32_e32 v44, 0xffff0000, v44
	v_and_b32_e32 v51, 0xffff0000, v40
	v_lshlrev_b32_e32 v40, 16, v45
	v_rcp_f32_e32 v49, v44
	v_rcp_f32_e32 v44, v40
	v_and_b32_e32 v40, 0xffff0000, v45
	v_rcp_f32_e32 v45, v40
	v_lshlrev_b32_e32 v40, 16, v41
	v_and_b32_e32 v41, 0xffff0000, v41
	v_rcp_f32_e32 v48, v48
	v_pk_mul_f32 v[40:41], v[44:45], v[40:41]
	v_lshlrev_b32_e32 v44, 16, v46
	v_and_b32_e32 v45, 0xffff0000, v46
	v_rcp_f32_e32 v44, v44
	v_rcp_f32_e32 v45, v45
	v_pk_mul_f32 v[48:49], v[48:49], v[50:51]
	v_lshlrev_b32_e32 v50, 16, v42
	v_and_b32_e32 v51, 0xffff0000, v42
	v_lshlrev_b32_e32 v42, 16, v47
	v_pk_mul_f32 v[50:51], v[44:45], v[50:51]
	v_rcp_f32_e32 v44, v42
	v_and_b32_e32 v42, 0xffff0000, v47
	v_rcp_f32_e32 v45, v42
	v_lshlrev_b32_e32 v42, 16, v43
	v_and_b32_e32 v43, 0xffff0000, v43
	v_pk_mul_f32 v[46:47], v[44:45], v[42:43]
	v_pk_mul_f32 v[44:45], v[38:39], v[40:41]
	v_pk_mul_f32 v[42:43], v[36:37], v[48:49]
	v_pk_mul_f32 v[46:47], v[34:35], v[46:47]
	v_pk_mul_f32 v[40:41], v[32:33], v[50:51]
.LBB0_709:
	v_add_u32_e32 v34, 0xa0, v184
	v_mov_b64_e32 v[32:33], s[58:59]
	v_mad_i64_i32 v[36:37], s[4:5], v34, s18, v[32:33]
	v_lshl_add_u64 v[34:35], v[36:37], 0, s[52:53]
	v_lshl_add_u64 v[32:33], v[36:37], 0, s[54:55]
	s_and_b64 vcc, exec, s[40:41]
	s_mov_b64 s[76:77], -1
	s_cbranch_vccnz .LBB0_711
	v_lshl_add_u64 v[38:39], v[34:35], 0, v[158:159]
	s_mov_b64 s[76:77], 0
	s_waitcnt vmcnt(15)
	v_mov_b32_e32 v48, v188
	v_mov_b32_e32 v49, v189
	v_mov_b32_e32 v50, v190
	v_mov_b32_e32 v51, v191
	v_lshlrev_b32_e32 v38, 16, v48
	v_and_b32_e32 v39, 0xffff0000, v48
	v_lshlrev_b32_e32 v48, 16, v49
	v_and_b32_e32 v49, 0xffff0000, v49
	v_lshlrev_b32_e32 v52, 16, v50
	v_and_b32_e32 v53, 0xffff0000, v50
	v_lshlrev_b32_e32 v50, 16, v51
	v_and_b32_e32 v51, 0xffff0000, v51
	v_pk_mul_f32 v[38:39], v[28:29], v[38:39]
	v_pk_mul_f32 v[54:55], v[30:31], v[48:49]
	v_pk_mul_f32 v[98:99], v[26:27], v[50:51]
	v_pk_mul_f32 v[50:51], v[24:25], v[52:53]
	v_cvt_pk_bf16_f32 v48, v38, v39
	v_lshl_add_u64 v[38:39], v[32:33], 0, v[158:159]
	v_cvt_pk_bf16_f32 v49, v54, v55
	v_cvt_pk_bf16_f32 v50, v50, v51
	v_cvt_pk_bf16_f32 v51, v98, v99
	global_store_dwordx4 v[38:39], v[48:51], off
.LBB0_711:
	v_lshl_add_u64 v[36:37], s[34:35], 1, v[36:37]
	v_lshl_add_u64 v[36:37], v[36:37], 0, s[60:61]
	v_mov_b32_e32 v98, 0
	s_andn2_b64 vcc, exec, s[76:77]
	v_lshl_add_u64 v[36:37], v[156:157], 1, v[36:37]
	v_mov_b32_e32 v99, 0
	v_mov_b32_e32 v104, 0
	v_mov_b32_e32 v105, 0
	v_mov_b32_e32 v100, 0
	v_mov_b32_e32 v101, 0
	v_mov_b32_e32 v102, 0
	v_mov_b32_e32 v103, 0
	s_cbranch_vccnz .LBB0_713
	s_waitcnt vmcnt(6)
	v_mov_b32_e32 v48, v188
	v_mov_b32_e32 v49, v189
	v_mov_b32_e32 v50, v190
	v_mov_b32_e32 v51, v191
	v_mov_b32_e32 v52, v192
	v_mov_b32_e32 v53, v193
	v_mov_b32_e32 v54, v194
	v_mov_b32_e32 v55, v195
	v_lshlrev_b32_e32 v98, 16, v48
	v_lshlrev_b32_e32 v38, 16, v52
	v_and_b32_e32 v39, 0xffff0000, v52
	v_and_b32_e32 v99, 0xffff0000, v48
	v_lshlrev_b32_e32 v48, 16, v53
	v_rcp_f32_e32 v38, v38
	v_rcp_f32_e32 v39, v39
	v_rcp_f32_e32 v52, v48
	v_and_b32_e32 v48, 0xffff0000, v53
	v_rcp_f32_e32 v53, v48
	v_pk_mul_f32 v[38:39], v[38:39], v[98:99]
	v_lshlrev_b32_e32 v48, 16, v49
	v_and_b32_e32 v49, 0xffff0000, v49
	v_lshlrev_b32_e32 v98, 16, v50
	v_and_b32_e32 v99, 0xffff0000, v50
	v_lshlrev_b32_e32 v50, 16, v55
	v_pk_mul_f32 v[48:49], v[52:53], v[48:49]
	v_lshlrev_b32_e32 v52, 16, v54
	v_and_b32_e32 v53, 0xffff0000, v54
	v_rcp_f32_e32 v54, v50
	v_and_b32_e32 v50, 0xffff0000, v55
	v_rcp_f32_e32 v52, v52
	v_rcp_f32_e32 v53, v53
	v_rcp_f32_e32 v55, v50
	v_lshlrev_b32_e32 v50, 16, v51
	v_and_b32_e32 v51, 0xffff0000, v51
	v_pk_mul_f32 v[52:53], v[52:53], v[98:99]
	v_pk_mul_f32 v[50:51], v[54:55], v[50:51]
	v_pk_mul_f32 v[102:103], v[30:31], v[48:49]
	v_pk_mul_f32 v[100:101], v[28:29], v[38:39]
	v_pk_mul_f32 v[104:105], v[26:27], v[50:51]
	v_pk_mul_f32 v[98:99], v[24:25], v[52:53]
; __device__ __forceinline__ unsigned cvt_pk_bf16(float lo, float hi) { unsigned r; asm volatile("v_cvt_pk_bf16_f32 %0, %1, %2" : "=v"(r) : "v"(lo), "v"(hi)); return r; }
; __device__ __forceinline__ float bf_lo(unsigned u) { return __uint_as_float(u << 16); }
; __device__ __forceinline__ float bf_hi(unsigned u) { return __uint_as_float(u & 0xffff0000u); }
;     __device__ __forceinline__ void operator()(f32x4 (&acc)[2][2][4][2], const Unit& u, int wr, int wc, int fr, int fq) const {
;     ...
;             for (int m = 0; m < 4; ++m) { bf16_t* hrow = H + (size_t)(row0 + ai * HALF + m * 16) * INC;
; #pragma unroll
;                 for (int bj = 0; bj < 2; ++bj) { const int col = col0 + bj * HALF;
;                     if (br < 2) {
;                         const u32x4 ga = *(const u32x4*)(hrow + C_GL + br * 1024 + col), gb = *(const u32x4*)(hrow + C_GL + (br + 1) * 1024 + col);
;                         float r[8];
; #pragma unroll
;                         for (int e = 0; e < 4; ++e) { const unsigned wa = ga[e], wb = gb[e];
;                             r[2 * e]     = bf_lo(wa) * __builtin_amdgcn_rcpf(bf_lo(wb));
;                             r[2 * e + 1] = bf_hi(wa) * __builtin_amdgcn_rcpf(bf_hi(wb)); }
;                         acc[ai][bj][m][0] *= (f32x4){r[0], r[1], r[2], r[3]}; acc[ai][bj][m][1] *= (f32x4){r[4], r[5], r[6], r[7]};
;                     } else {
;                         const u32x4 gc = *(const u32x4*)(hrow + C_GL + 2048 + col);
;                         f32x4 g0, g1;
;                         g0[0] = bf_lo(gc.x); g0[1] = bf_hi(gc.x); g0[2] = bf_lo(gc.y); g0[3] = bf_hi(gc.y);
;                         g1[0] = bf_lo(gc.z); g1[1] = bf_hi(gc.z); g1[2] = bf_lo(gc.w); g1[3] = bf_hi(gc.w);
;                         const f32x4 v0 = acc[ai][bj][m][0] * g0, v1 = acc[ai][bj][m][1] * g1;
;                         u32x4 w; w.x = cvt_pk_bf16(v0[0], v0[1]); w.y = cvt_pk_bf16(v0[2], v0[3]); w.z = cvt_pk_bf16(v1[0], v1[1]); w.w = cvt_pk_bf16(v1[2], v1[3]);
;                         *(u32x4*)(hrow + C_AZ + col) = w;
;                         acc[ai][bj][m][0] = (f32x4){0.f, 0.f, 0.f, 0.f}; acc[ai][bj][m][1] = (f32x4){0.f, 0.f, 0.f, 0.f};
;                     }
.LBB0_713:
	s_and_b64 vcc, exec, s[40:41]
	s_mov_b64 s[76:77], -1
	s_cbranch_vccnz .LBB0_715
	v_lshl_add_u64 v[24:25], v[34:35], 0, v[160:161]
	v_lshl_add_u64 v[28:29], v[32:33], 0, v[160:161]
	s_mov_b64 s[76:77], 0
	s_waitcnt vmcnt(14)
	v_mov_b32_e32 v24, v192
	v_mov_b32_e32 v25, v193
	v_mov_b32_e32 v26, v194
	v_mov_b32_e32 v27, v195
	v_lshlrev_b32_e32 v30, 16, v24
	v_and_b32_e32 v31, 0xffff0000, v24
	v_lshlrev_b32_e32 v24, 16, v25
	v_and_b32_e32 v25, 0xffff0000, v25
	v_lshlrev_b32_e32 v32, 16, v26
	v_and_b32_e32 v33, 0xffff0000, v26
	v_lshlrev_b32_e32 v26, 16, v27
	v_and_b32_e32 v27, 0xffff0000, v27
	v_pk_mul_f32 v[34:35], v[22:23], v[24:25]
	v_pk_mul_f32 v[24:25], v[20:21], v[30:31]
	v_pk_mul_f32 v[30:31], v[18:19], v[26:27]
	v_pk_mul_f32 v[26:27], v[16:17], v[32:33]
	v_cvt_pk_bf16_f32 v24, v24, v25
	v_cvt_pk_bf16_f32 v25, v34, v35
	s_nop 0
	v_cvt_pk_bf16_f32 v26, v26, v27
	v_cvt_pk_bf16_f32 v27, v30, v31
	global_store_dwordx4 v[28:29], v[24:27], off
.LBB0_715:
	s_nop 1
	v_mov_b32_e32 v24, 0
	s_andn2_b64 vcc, exec, s[76:77]
	v_mov_b32_e32 v25, 0
	v_mov_b32_e32 v30, 0
	v_mov_b32_e32 v31, 0
	v_mov_b32_e32 v26, 0
	v_mov_b32_e32 v27, 0
	v_mov_b32_e32 v28, 0
	v_mov_b32_e32 v29, 0
	s_cbranch_vccnz .LBB0_717
	s_waitcnt vmcnt(4)
	v_mov_b32_e32 v24, v196
	v_mov_b32_e32 v25, v197
	v_mov_b32_e32 v26, v198
	v_mov_b32_e32 v27, v199
	v_mov_b32_e32 v28, v212
	v_mov_b32_e32 v29, v213
	v_mov_b32_e32 v30, v214
	v_mov_b32_e32 v31, v215
	v_lshlrev_b32_e32 v34, 16, v24
	v_lshlrev_b32_e32 v32, 16, v28
	v_and_b32_e32 v28, 0xffff0000, v28
	v_and_b32_e32 v35, 0xffff0000, v24
	v_lshlrev_b32_e32 v24, 16, v29
	v_rcp_f32_e32 v33, v28
	v_rcp_f32_e32 v28, v24
	v_and_b32_e32 v24, 0xffff0000, v29
	v_rcp_f32_e32 v29, v24
	v_lshlrev_b32_e32 v24, 16, v25
	v_and_b32_e32 v25, 0xffff0000, v25
	v_rcp_f32_e32 v32, v32
	v_pk_mul_f32 v[24:25], v[28:29], v[24:25]
	v_lshlrev_b32_e32 v28, 16, v30
	v_and_b32_e32 v29, 0xffff0000, v30
	v_rcp_f32_e32 v28, v28
	v_rcp_f32_e32 v29, v29
	v_pk_mul_f32 v[32:33], v[32:33], v[34:35]
	v_lshlrev_b32_e32 v34, 16, v26
	v_and_b32_e32 v35, 0xffff0000, v26
	v_lshlrev_b32_e32 v26, 16, v31
	v_pk_mul_f32 v[34:35], v[28:29], v[34:35]
	v_rcp_f32_e32 v28, v26
	v_and_b32_e32 v26, 0xffff0000, v31
	v_rcp_f32_e32 v29, v26
	v_lshlrev_b32_e32 v26, 16, v27
	v_and_b32_e32 v27, 0xffff0000, v27
	v_pk_mul_f32 v[30:31], v[28:29], v[26:27]
	v_pk_mul_f32 v[28:29], v[22:23], v[24:25]
	v_pk_mul_f32 v[26:27], v[20:21], v[32:33]
	v_pk_mul_f32 v[30:31], v[18:19], v[30:31]
	v_pk_mul_f32 v[24:25], v[16:17], v[34:35]
.LBB0_717:
	v_add_u32_e32 v18, 0xb0, v184
	v_mov_b64_e32 v[16:17], s[58:59]
	v_mad_i64_i32 v[18:19], s[4:5], v18, s18, v[16:17]
	v_lshl_add_u64 v[20:21], v[18:19], 0, s[52:53]
	v_lshl_add_u64 v[16:17], v[18:19], 0, s[54:55]
	s_and_b64 vcc, exec, s[40:41]
	s_mov_b64 s[76:77], -1
	s_cbranch_vccnz .LBB0_719
	v_lshl_add_u64 v[22:23], v[20:21], 0, v[158:159]
	v_lshl_add_u64 v[22:23], v[16:17], 0, v[158:159]
	s_mov_b64 s[76:77], 0
	s_waitcnt vmcnt(13)
	v_mov_b32_e32 v32, v196
	v_mov_b32_e32 v33, v197
	v_mov_b32_e32 v34, v198
	v_mov_b32_e32 v35, v199
	v_lshlrev_b32_e32 v36, 16, v32
	v_and_b32_e32 v37, 0xffff0000, v32
	v_lshlrev_b32_e32 v32, 16, v33
	v_and_b32_e32 v33, 0xffff0000, v33
	v_lshlrev_b32_e32 v38, 16, v34
	v_and_b32_e32 v39, 0xffff0000, v34
	v_lshlrev_b32_e32 v34, 16, v35
	v_and_b32_e32 v35, 0xffff0000, v35
	v_pk_mul_f32 v[48:49], v[14:15], v[32:33]
	v_pk_mul_f32 v[32:33], v[12:13], v[36:37]
	v_pk_mul_f32 v[36:37], v[10:11], v[34:35]
	v_pk_mul_f32 v[34:35], v[8:9], v[38:39]
	v_cvt_pk_bf16_f32 v32, v32, v33
	v_cvt_pk_bf16_f32 v33, v48, v49
	s_nop 0
	v_cvt_pk_bf16_f32 v34, v34, v35
	v_cvt_pk_bf16_f32 v35, v36, v37
	global_store_dwordx4 v[22:23], v[32:35], off
; __device__ __forceinline__ unsigned cvt_pk_bf16(float lo, float hi) { unsigned r; asm volatile("v_cvt_pk_bf16_f32 %0, %1, %2" : "=v"(r) : "v"(lo), "v"(hi)); return r; }
; __device__ __forceinline__ float bf_lo(unsigned u) { return __uint_as_float(u << 16); }
; __device__ __forceinline__ float bf_hi(unsigned u) { return __uint_as_float(u & 0xffff0000u); }
;     __device__ __forceinline__ void operator()(f32x4 (&acc)[2][2][4][2], const Unit& u, int wr, int wc, int fr, int fq) const {
;     ...
;             for (int m = 0; m < 4; ++m) { bf16_t* hrow = H + (size_t)(row0 + ai * HALF + m * 16) * INC;
; #pragma unroll
;                 for (int bj = 0; bj < 2; ++bj) { const int col = col0 + bj * HALF;
;                     if (br < 2) {
;                         const u32x4 ga = *(const u32x4*)(hrow + C_GL + br * 1024 + col), gb = *(const u32x4*)(hrow + C_GL + (br + 1) * 1024 + col);
;                         float r[8];
; #pragma unroll
;                         for (int e = 0; e < 4; ++e) { const unsigned wa = ga[e], wb = gb[e];
;                             r[2 * e]     = bf_lo(wa) * __builtin_amdgcn_rcpf(bf_lo(wb));
;                             r[2 * e + 1] = bf_hi(wa) * __builtin_amdgcn_rcpf(bf_hi(wb)); }
;                         acc[ai][bj][m][0] *= (f32x4){r[0], r[1], r[2], r[3]}; acc[ai][bj][m][1] *= (f32x4){r[4], r[5], r[6], r[7]};
;                     } else {
;                         const u32x4 gc = *(const u32x4*)(hrow + C_GL + 2048 + col);
;                         f32x4 g0, g1;
;                         g0[0] = bf_lo(gc.x); g0[1] = bf_hi(gc.x); g0[2] = bf_lo(gc.y); g0[3] = bf_hi(gc.y);
;                         g1[0] = bf_lo(gc.z); g1[1] = bf_hi(gc.z); g1[2] = bf_lo(gc.w); g1[3] = bf_hi(gc.w);
;                         const f32x4 v0 = acc[ai][bj][m][0] * g0, v1 = acc[ai][bj][m][1] * g1;
;                         u32x4 w; w.x = cvt_pk_bf16(v0[0], v0[1]); w.y = cvt_pk_bf16(v0[2], v0[3]); w.z = cvt_pk_bf16(v1[0], v1[1]); w.w = cvt_pk_bf16(v1[2], v1[3]);
;                         *(u32x4*)(hrow + C_AZ + col) = w;
;                         acc[ai][bj][m][0] = (f32x4){0.f, 0.f, 0.f, 0.f}; acc[ai][bj][m][1] = (f32x4){0.f, 0.f, 0.f, 0.f};
;                     }
.LBB0_719:
	v_lshl_add_u64 v[18:19], s[34:35], 1, v[18:19]
	v_lshl_add_u64 v[18:19], v[18:19], 0, s[60:61]
	v_mov_b32_e32 v114, 0
	s_andn2_b64 vcc, exec, s[76:77]
	v_lshl_add_u64 v[18:19], v[156:157], 1, v[18:19]
	v_mov_b32_e32 v115, 0
	v_mov_b32_e32 v120, 0
	v_mov_b32_e32 v121, 0
	v_mov_b32_e32 v116, 0
	v_mov_b32_e32 v117, 0
	v_mov_b32_e32 v118, 0
	v_mov_b32_e32 v119, 0
	s_cbranch_vccnz .LBB0_721
	s_waitcnt vmcnt(2)
	v_mov_b32_e32 v32, v216
	v_mov_b32_e32 v33, v217
	v_mov_b32_e32 v34, v218
	v_mov_b32_e32 v35, v219
	v_mov_b32_e32 v36, v220
	v_mov_b32_e32 v37, v221
	v_mov_b32_e32 v38, v222
	v_mov_b32_e32 v39, v223
	v_lshlrev_b32_e32 v48, 16, v32
	v_lshlrev_b32_e32 v22, 16, v36
	v_and_b32_e32 v23, 0xffff0000, v36
	v_and_b32_e32 v49, 0xffff0000, v32
	v_lshlrev_b32_e32 v32, 16, v37
	v_rcp_f32_e32 v22, v22
	v_rcp_f32_e32 v23, v23
	v_rcp_f32_e32 v36, v32
	v_and_b32_e32 v32, 0xffff0000, v37
	v_rcp_f32_e32 v37, v32
	v_pk_mul_f32 v[22:23], v[22:23], v[48:49]
	v_lshlrev_b32_e32 v32, 16, v33
	v_and_b32_e32 v33, 0xffff0000, v33
	v_lshlrev_b32_e32 v48, 16, v34
	v_and_b32_e32 v49, 0xffff0000, v34
	v_lshlrev_b32_e32 v34, 16, v39
	v_pk_mul_f32 v[32:33], v[36:37], v[32:33]
	v_lshlrev_b32_e32 v36, 16, v38
	v_and_b32_e32 v37, 0xffff0000, v38
	v_rcp_f32_e32 v38, v34
	v_and_b32_e32 v34, 0xffff0000, v39
	v_rcp_f32_e32 v36, v36
	v_rcp_f32_e32 v37, v37
	v_rcp_f32_e32 v39, v34
	v_lshlrev_b32_e32 v34, 16, v35
	v_and_b32_e32 v35, 0xffff0000, v35
	v_pk_mul_f32 v[36:37], v[36:37], v[48:49]
	v_pk_mul_f32 v[34:35], v[38:39], v[34:35]
	v_pk_mul_f32 v[118:119], v[14:15], v[32:33]
	v_pk_mul_f32 v[116:117], v[12:13], v[22:23]
	v_pk_mul_f32 v[120:121], v[10:11], v[34:35]
	v_pk_mul_f32 v[114:115], v[8:9], v[36:37]
.LBB0_721:
	s_and_b64 vcc, exec, s[40:41]
	s_mov_b64 s[34:35], -1
	s_cbranch_vccnz .LBB0_723
	v_lshl_add_u64 v[8:9], v[20:21], 0, v[160:161]
	v_lshl_add_u64 v[12:13], v[16:17], 0, v[160:161]
	s_mov_b64 s[34:35], 0
	s_waitcnt vmcnt(12)
	v_mov_b32_e32 v8, v212
	v_mov_b32_e32 v9, v213
	v_mov_b32_e32 v10, v214
	v_mov_b32_e32 v11, v215
	v_lshlrev_b32_e32 v14, 16, v8
	v_and_b32_e32 v15, 0xffff0000, v8
	v_lshlrev_b32_e32 v8, 16, v9
	v_and_b32_e32 v9, 0xffff0000, v9
	v_lshlrev_b32_e32 v16, 16, v10
	v_and_b32_e32 v17, 0xffff0000, v10
	v_lshlrev_b32_e32 v10, 16, v11
	v_and_b32_e32 v11, 0xffff0000, v11
	v_pk_mul_f32 v[20:21], v[6:7], v[8:9]
	v_pk_mul_f32 v[8:9], v[4:5], v[14:15]
	v_pk_mul_f32 v[14:15], v[2:3], v[10:11]
	v_pk_mul_f32 v[10:11], v[0:1], v[16:17]
	v_cvt_pk_bf16_f32 v8, v8, v9
	v_cvt_pk_bf16_f32 v9, v20, v21
	s_nop 0
	v_cvt_pk_bf16_f32 v10, v10, v11
	v_cvt_pk_bf16_f32 v11, v14, v15
	global_store_dwordx4 v[12:13], v[8:11], off
.LBB0_723:
	s_nop 1
	v_mov_b32_e32 v8, 0
	s_andn2_b64 vcc, exec, s[34:35]
	v_mov_b32_e32 v9, 0
	v_mov_b32_e32 v14, 0
	v_mov_b32_e32 v15, 0
	v_mov_b32_e32 v10, 0
	v_mov_b32_e32 v11, 0
	v_mov_b32_e32 v12, 0
	v_mov_b32_e32 v13, 0
	s_cbranch_vccnz .LBB0_725
	s_waitcnt vmcnt(0)
	v_mov_b32_e32 v8, v224
	v_mov_b32_e32 v9, v225
	v_mov_b32_e32 v10, v226
	v_mov_b32_e32 v11, v227
	v_mov_b32_e32 v12, v228
	v_mov_b32_e32 v13, v229
	v_mov_b32_e32 v14, v230
	v_mov_b32_e32 v15, v231
	v_lshlrev_b32_e32 v18, 16, v8
	v_lshlrev_b32_e32 v16, 16, v12
	v_and_b32_e32 v12, 0xffff0000, v12
	v_and_b32_e32 v19, 0xffff0000, v8
	v_lshlrev_b32_e32 v8, 16, v13
	v_rcp_f32_e32 v17, v12
	v_rcp_f32_e32 v12, v8
	v_and_b32_e32 v8, 0xffff0000, v13
	v_rcp_f32_e32 v13, v8
	v_lshlrev_b32_e32 v8, 16, v9
	v_and_b32_e32 v9, 0xffff0000, v9
	v_rcp_f32_e32 v16, v16
	v_pk_mul_f32 v[8:9], v[12:13], v[8:9]
	v_lshlrev_b32_e32 v12, 16, v14
	v_and_b32_e32 v13, 0xffff0000, v14
	v_rcp_f32_e32 v12, v12
	v_rcp_f32_e32 v13, v13
	v_pk_mul_f32 v[16:17], v[16:17], v[18:19]
	v_lshlrev_b32_e32 v18, 16, v10
	v_and_b32_e32 v19, 0xffff0000, v10
	v_lshlrev_b32_e32 v10, 16, v15
	v_pk_mul_f32 v[18:19], v[12:13], v[18:19]
	v_rcp_f32_e32 v12, v10
	v_and_b32_e32 v10, 0xffff0000, v15
	v_rcp_f32_e32 v13, v10
	v_lshlrev_b32_e32 v10, 16, v11
	v_and_b32_e32 v11, 0xffff0000, v11
	v_pk_mul_f32 v[14:15], v[12:13], v[10:11]
	v_pk_mul_f32 v[12:13], v[6:7], v[8:9]
	v_pk_mul_f32 v[10:11], v[4:5], v[16:17]
	v_pk_mul_f32 v[14:15], v[2:3], v[14:15]
	v_pk_mul_f32 v[8:9], v[0:1], v[18:19]
